# BAR steps: first v_exp group issued between the post-barrier K ds_reads and the first QK MFMA (covers LDS latency)
# speedup vs baseline: 1.0061x; 1.0061x over previous
.LBB0_641:
	s_add_i32 s24, s23, -7
	s_lshl_b32 s92, s24, 13
	s_add_u32 vcc_lo, s100, s92
	s_addc_u32 vcc_hi, s101, 0
	global_load_dwordx4 v[52:55], v248, vcc
	s_add_i32 s24, s23, -8
	s_lshl_b32 s92, s24, 7
	s_add_u32 vcc_lo, s98, s92
	s_addc_u32 vcc_hi, s99, 0
	global_load_dwordx4 v[56:59], v249, vcc
	s_mul_i32 s26, s25, 0x2400
	s_add_i32 s24, s23, -7
	s_add_i32 s27, s26, 0xffffdc00
	s_cmp_lg_u32 s25, 0
	s_cselect_b32 s27, s27, 0x9000
	v_add_u32_e32 v1, s27, v163
	ds_read_b128 v[60:63], v1 offset:36864
	ds_read_b128 v[114:117], v1 offset:36896
	ds_read_b128 v[118:121], v1 offset:41472
	ds_read_b128 v[134:137], v1 offset:41504
	ds_read_b128 v[146:149], v1 offset:36928
	ds_read_b128 v[150:153], v1 offset:36960
	ds_read_b128 v[196:199], v1 offset:41536
	ds_read_b128 v[200:203], v1 offset:41568
	s_setprio 3
	v_cvt_pk_bf16_f32 v204, v102, v103
	v_cvt_pk_bf16_f32 v205, v104, v105
	v_cvt_pk_bf16_f32 v206, v98, v99
	v_cvt_pk_bf16_f32 v207, v100, v101
	s_waitcnt lgkmcnt(7)
	s_nop 0
	v_mfma_f32_32x32x16_bf16 v[18:33], v[60:63], v[204:207], v[18:33]
	v_add_f32_e32 v1, v102, v103
	v_add_f32_e32 v1, v1, v104
	v_add_f32_e32 v1, v1, v105
	s_waitcnt lgkmcnt(5)
	v_mfma_f32_32x32x16_bf16 v[2:17], v[118:121], v[204:207], v[2:17]
	v_cvt_pk_bf16_f32 v60, v194, v187
	v_cvt_pk_bf16_f32 v61, v186, v185
	v_cvt_pk_bf16_f32 v62, v133, v132
	v_cvt_pk_bf16_f32 v63, v131, v130
	v_add_f32_e32 v1, v1, v98
	v_add_f32_e32 v1, v1, v99
	v_add_f32_e32 v1, v1, v100
	v_add_f32_e32 v1, v1, v101
	s_nop 0
	v_mfma_f32_32x32x16_bf16 v[18:33], v[114:117], v[60:63], v[18:33]
	v_add_f32_e32 v1, v1, v194
	v_add_f32_e32 v1, v1, v187
	v_add_f32_e32 v1, v1, v186
	v_add_f32_e32 v1, v1, v185
	s_waitcnt lgkmcnt(4)
	v_mfma_f32_32x32x16_bf16 v[2:17], v[134:137], v[60:63], v[2:17]
	v_cvt_pk_bf16_f32 v98, v129, v128
	v_cvt_pk_bf16_f32 v99, v127, v126
	v_cvt_pk_bf16_f32 v100, v125, v124
	v_cvt_pk_bf16_f32 v101, v123, v122
	v_add_f32_e32 v1, v1, v133
	v_add_f32_e32 v1, v1, v132
	v_add_f32_e32 v1, v1, v131
	v_add_f32_e32 v1, v1, v130
	s_waitcnt lgkmcnt(3)
	v_mfma_f32_32x32x16_bf16 v[18:33], v[146:149], v[98:101], v[18:33]
	v_add_f32_e32 v1, v1, v129
	v_add_f32_e32 v1, v1, v128
	v_add_f32_e32 v1, v1, v127
	v_add_f32_e32 v1, v1, v126
	s_waitcnt lgkmcnt(1)
	v_mfma_f32_32x32x16_bf16 v[2:17], v[196:199], v[98:101], v[2:17]
	v_cvt_pk_bf16_f32 v60, v109, v108
	v_cvt_pk_bf16_f32 v61, v107, v106
	v_cvt_pk_bf16_f32 v62, v113, v112
	v_cvt_pk_bf16_f32 v63, v111, v110
	v_add_f32_e32 v1, v1, v125
	v_add_f32_e32 v1, v1, v124
	v_add_f32_e32 v1, v1, v123
	v_add_f32_e32 v1, v1, v122
	s_nop 0
	v_mfma_f32_32x32x16_bf16 v[18:33], v[150:153], v[60:63], v[18:33]
	v_add_f32_e32 v1, v1, v109
	v_add_f32_e32 v1, v1, v108
	v_add_f32_e32 v1, v1, v107
	v_add_f32_e32 v1, v1, v106
	s_waitcnt lgkmcnt(0)
	v_mfma_f32_32x32x16_bf16 v[2:17], v[200:203], v[60:63], v[2:17]
	v_add_f32_e32 v1, v1, v113
	v_add_f32_e32 v1, v1, v112
	v_add_f32_e32 v1, v1, v111
	v_add_f32_e32 v1, v1, v110
	s_setprio 2
	s_waitcnt lgkmcnt(0)
	s_barrier
	ds_read_b128 v[240:243], v165 offset:18432
	ds_read_b128 v[244:247], v165 offset:23040
	ds_read_b128 v[130:133], v165 offset:18464
	ds_read_b128 v[146:149], v165 offset:23072
	v_exp_f32_e32 v185, v82
	v_exp_f32_e32 v186, v83
	v_exp_f32_e32 v187, v84
	v_exp_f32_e32 v194, v85
	v_exp_f32_e32 v195, v86
	v_exp_f32_e32 v196, v87
	v_exp_f32_e32 v197, v88
	v_exp_f32_e32 v198, v89
	s_waitcnt lgkmcnt(2)
	v_mfma_f32_32x32x16_bf16 v[114:129], v[240:243], v[158:161], v[34:49]
	s_waitcnt lgkmcnt(1)
	v_mfma_f32_32x32x16_bf16 v[98:113], v[244:247], v[158:161], v[34:49]
	v_exp_f32_e32 v199, v90
	v_exp_f32_e32 v200, v91
	v_exp_f32_e32 v201, v92
	v_exp_f32_e32 v202, v93
	v_exp_f32_e32 v134, v94
	v_exp_f32_e32 v135, v95
	v_exp_f32_e32 v136, v96
	v_exp_f32_e32 v137, v97
	v_mfma_f32_32x32x16_bf16 v[114:129], v[130:133], v[154:157], v[114:129]
	v_exp_f32_e32 v96, v66
	v_exp_f32_e32 v97, v67
	v_exp_f32_e32 v203, v68
	v_exp_f32_e32 v204, v69
	v_exp_f32_e32 v130, v70
	v_exp_f32_e32 v131, v71
	v_exp_f32_e32 v132, v72
	v_exp_f32_e32 v133, v73
	s_waitcnt lgkmcnt(0)
	v_mfma_f32_32x32x16_bf16 v[98:113], v[146:149], v[154:157], v[98:113]
	v_exp_f32_e32 v205, v74
	v_exp_f32_e32 v206, v75
	v_exp_f32_e32 v207, v76
	v_exp_f32_e32 v208, v77
	v_exp_f32_e32 v209, v78
	v_exp_f32_e32 v210, v79
	v_exp_f32_e32 v211, v80
	v_exp_f32_e32 v212, v81
	v_add_u32_e32 v88, s26, v163
	ds_read_b128 v[240:243], v165 offset:27648
	ds_read_b128 v[244:247], v165 offset:32256
	ds_read_b128 v[60:63], v88 offset:41472
	ds_read_b128 v[64:67], v88 offset:36864
	ds_read_b128 v[68:71], v88 offset:36896
	ds_read_b128 v[72:75], v88 offset:41504
	ds_read_b128 v[76:79], v88 offset:36928
	ds_read_b128 v[80:83], v88 offset:41536
	ds_read_b128 v[84:87], v88 offset:36960
	ds_read_b128 v[88:91], v88 offset:41568
	s_cmp_gt_i32 s25, 2
	s_cselect_b32 s27, -3, 2
	s_add_i32 s27, s27, s25
	s_add_i32 s26, s23, -6
	s_mulk_i32 s27, 0x2400
	s_min_u32 s26, s26, s13
	v_add_u32_e32 v51, s27, v182
	s_min_u32 s24, s24, s13
	s_lshl_b32 s92, s26, 13
	s_waitcnt vmcnt(3)
	ds_write_b128 v182, v[138:141]
	s_waitcnt vmcnt(2)
	ds_write_b128 v51, v[142:145] offset:36864
	v_add_f32_e32 v1, v50, v1
	s_add_u32 vcc_lo, s100, s92
	s_addc_u32 vcc_hi, s101, 0
	global_load_dwordx4 v[146:149], v248, vcc
	s_lshl_b32 s92, s24, 7
	s_add_u32 vcc_lo, s98, s92
	s_addc_u32 vcc_hi, s99, 0
	global_load_dwordx4 v[150:153], v249, vcc
	s_add_i32 s27, s25, 1
	s_setprio 1
	v_cvt_pk_bf16_f32 v92, v185, v186
	v_cvt_pk_bf16_f32 v93, v187, v194
	v_cvt_pk_bf16_f32 v94, v195, v196
	v_cvt_pk_bf16_f32 v95, v197, v198
	s_waitcnt lgkmcnt(8)
	s_nop 0
	v_mfma_f32_32x32x16_bf16 v[18:33], v[64:67], v[92:95], v[18:33]
	v_add_f32_e32 v213, v185, v186
	v_add_f32_e32 v213, v213, v187
	v_add_f32_e32 v213, v213, v194
	s_nop 0
	v_mfma_f32_32x32x16_bf16 v[2:17], v[60:63], v[92:95], v[2:17]
	v_cvt_pk_bf16_f32 v64, v199, v200
	v_cvt_pk_bf16_f32 v65, v201, v202
	v_cvt_pk_bf16_f32 v66, v134, v135
	v_cvt_pk_bf16_f32 v67, v136, v137
	v_add_f32_e32 v213, v213, v195
	v_add_f32_e32 v213, v213, v196
	v_add_f32_e32 v213, v213, v197
	v_add_f32_e32 v213, v213, v198
	s_waitcnt lgkmcnt(7)
	v_mfma_f32_32x32x16_bf16 v[18:33], v[68:71], v[64:67], v[18:33]
	v_add_f32_e32 v213, v213, v199
	v_add_f32_e32 v213, v213, v200
	v_add_f32_e32 v213, v213, v201
	v_add_f32_e32 v213, v213, v202
	s_waitcnt lgkmcnt(6)
	v_mfma_f32_32x32x16_bf16 v[2:17], v[72:75], v[64:67], v[2:17]
	v_cvt_pk_bf16_f32 v60, v96, v97
	v_cvt_pk_bf16_f32 v61, v203, v204
	v_cvt_pk_bf16_f32 v62, v130, v131
	v_cvt_pk_bf16_f32 v63, v132, v133
	v_add_f32_e32 v213, v213, v134
	v_add_f32_e32 v213, v213, v135
	v_add_f32_e32 v213, v213, v136
	v_add_f32_e32 v213, v213, v137
	s_waitcnt lgkmcnt(5)
	v_mfma_f32_32x32x16_bf16 v[18:33], v[76:79], v[60:63], v[18:33]
	v_add_f32_e32 v213, v213, v96
	v_add_f32_e32 v213, v213, v97
	v_add_f32_e32 v213, v213, v203
	v_add_f32_e32 v213, v213, v204
	s_waitcnt lgkmcnt(4)
	v_mfma_f32_32x32x16_bf16 v[2:17], v[80:83], v[60:63], v[2:17]
	v_cvt_pk_bf16_f32 v64, v205, v206
	v_cvt_pk_bf16_f32 v65, v207, v208
	v_cvt_pk_bf16_f32 v66, v209, v210
	v_cvt_pk_bf16_f32 v67, v211, v212
	v_add_f32_e32 v213, v213, v130
	v_add_f32_e32 v213, v213, v131
	v_add_f32_e32 v213, v213, v132
	v_add_f32_e32 v213, v213, v133
	s_waitcnt lgkmcnt(3)
	v_mfma_f32_32x32x16_bf16 v[18:33], v[84:87], v[64:67], v[18:33]
	v_add_f32_e32 v213, v213, v205
	v_add_f32_e32 v213, v213, v206
	v_add_f32_e32 v213, v213, v207
	v_add_f32_e32 v213, v213, v208
	s_waitcnt lgkmcnt(2)
	v_mfma_f32_32x32x16_bf16 v[2:17], v[88:91], v[64:67], v[2:17]
	v_add_f32_e32 v213, v213, v209
	v_add_f32_e32 v213, v213, v210
	v_add_f32_e32 v213, v213, v211
	v_add_f32_e32 v213, v213, v212
	s_setprio 0
	ds_read_b128 v[64:67], v165 offset:27680
	ds_read_b128 v[72:75], v165 offset:32288
	s_cmp_lg_u32 s25, 4
	s_cselect_b32 s24, s27, 0
	s_waitcnt lgkmcnt(2)
	v_mfma_f32_32x32x16_bf16 v[130:145], v[240:243], v[158:161], v[34:49]
	v_exp_f32_e32 v185, v114
	v_exp_f32_e32 v186, v115
	v_exp_f32_e32 v187, v116
	v_exp_f32_e32 v194, v117
	v_exp_f32_e32 v195, v118
	v_exp_f32_e32 v196, v119
	v_exp_f32_e32 v197, v120
	v_exp_f32_e32 v198, v121
	s_waitcnt lgkmcnt(1)
	v_mfma_f32_32x32x16_bf16 v[82:97], v[244:247], v[158:161], v[34:49]
	v_exp_f32_e32 v199, v122
	v_exp_f32_e32 v200, v123
	v_exp_f32_e32 v201, v124
	v_exp_f32_e32 v202, v125
	v_exp_f32_e32 v122, v126
	v_exp_f32_e32 v123, v127
	v_exp_f32_e32 v124, v128
	v_exp_f32_e32 v125, v129
	v_mfma_f32_32x32x16_bf16 v[130:145], v[64:67], v[154:157], v[130:145]
	v_exp_f32_e32 v126, v98
	v_exp_f32_e32 v127, v99
	v_exp_f32_e32 v128, v100
	v_exp_f32_e32 v129, v101
	v_exp_f32_e32 v203, v102
	v_exp_f32_e32 v204, v103
	v_exp_f32_e32 v205, v104
	v_exp_f32_e32 v206, v105
	s_waitcnt lgkmcnt(0)
	v_mfma_f32_32x32x16_bf16 v[82:97], v[72:75], v[154:157], v[82:97]
	v_exp_f32_e32 v102, v106
	v_exp_f32_e32 v103, v107
	v_exp_f32_e32 v104, v108
	v_exp_f32_e32 v105, v109
	v_exp_f32_e32 v106, v110
	v_exp_f32_e32 v107, v111
	v_exp_f32_e32 v108, v112
	v_exp_f32_e32 v109, v113
	s_cmp_gt_i32 s24, 2
	s_cselect_b32 s25, -3, 2
	s_add_i32 s25, s25, s24
	s_mulk_i32 s25, 0x2400
	v_add_u32_e32 v50, s25, v182
	s_add_i32 s25, s24, 1
	s_cmp_lg_u32 s24, 4
	s_cselect_b32 s24, s25, 0
	s_add_i32 s25, s23, -5
	s_min_u32 s25, s25, s13
	s_lshl_b32 s92, s25, 13
	s_waitcnt vmcnt(3)
	ds_write_b128 v182, v[52:55] offset:9216
	s_waitcnt vmcnt(2)
	ds_write_b128 v50, v[56:59] offset:36864
	s_add_u32 vcc_lo, s100, s92
	s_addc_u32 vcc_hi, s101, 0
	global_load_dwordx4 v[118:121], v248, vcc
	s_lshl_b32 s92, s26, 7
	s_add_u32 vcc_lo, s98, s92
	s_addc_u32 vcc_hi, s99, 0
	global_load_dwordx4 v[114:117], v249, vcc
	s_mul_i32 s26, s24, 0x2400
	s_add_i32 s27, s26, 0xffffdc00
	s_cmp_lg_u32 s24, 0
	s_cselect_b32 s27, s27, 0x9000
	v_add_u32_e32 v78, s27, v163
	ds_read_b128 v[50:53], v78 offset:36864
	ds_read_b128 v[54:57], v78 offset:36896
	ds_read_b128 v[58:61], v78 offset:41472
	ds_read_b128 v[62:65], v78 offset:41504
	ds_read_b128 v[66:69], v78 offset:36928
	ds_read_b128 v[70:73], v78 offset:36960
	ds_read_b128 v[74:77], v78 offset:41536
	ds_read_b128 v[78:81], v78 offset:41568
	s_setprio 3
	v_cvt_pk_bf16_f32 v98, v185, v186
	v_cvt_pk_bf16_f32 v99, v187, v194
	v_cvt_pk_bf16_f32 v100, v195, v196
	v_cvt_pk_bf16_f32 v101, v197, v198
	s_waitcnt lgkmcnt(7)
	s_nop 0
	v_mfma_f32_32x32x16_bf16 v[18:33], v[50:53], v[98:101], v[18:33]
	v_add_f32_e32 v110, v185, v186
	v_add_f32_e32 v110, v110, v187
	v_add_f32_e32 v110, v110, v194
	s_waitcnt lgkmcnt(5)
	v_mfma_f32_32x32x16_bf16 v[2:17], v[58:61], v[98:101], v[2:17]
	v_cvt_pk_bf16_f32 v50, v199, v200
	v_cvt_pk_bf16_f32 v51, v201, v202
	v_cvt_pk_bf16_f32 v52, v122, v123
	v_cvt_pk_bf16_f32 v53, v124, v125
	v_add_f32_e32 v110, v110, v195
	v_add_f32_e32 v110, v110, v196
	v_add_f32_e32 v110, v110, v197
	v_add_f32_e32 v110, v110, v198
	s_nop 0
	v_mfma_f32_32x32x16_bf16 v[18:33], v[54:57], v[50:53], v[18:33]
	v_add_f32_e32 v110, v110, v199
	v_add_f32_e32 v110, v110, v200
	v_add_f32_e32 v110, v110, v201
	v_add_f32_e32 v110, v110, v202
	s_waitcnt lgkmcnt(4)
	v_mfma_f32_32x32x16_bf16 v[2:17], v[62:65], v[50:53], v[2:17]
	v_cvt_pk_bf16_f32 v54, v126, v127
	v_cvt_pk_bf16_f32 v55, v128, v129
	v_cvt_pk_bf16_f32 v56, v203, v204
	v_cvt_pk_bf16_f32 v57, v205, v206
	v_add_f32_e32 v110, v110, v122
	v_add_f32_e32 v110, v110, v123
	v_add_f32_e32 v110, v110, v124
	v_add_f32_e32 v110, v110, v125
	s_waitcnt lgkmcnt(3)
	v_mfma_f32_32x32x16_bf16 v[18:33], v[66:69], v[54:57], v[18:33]
	v_add_f32_e32 v110, v110, v126
	v_add_f32_e32 v110, v110, v127
	v_add_f32_e32 v110, v110, v128
	v_add_f32_e32 v110, v110, v129
	s_waitcnt lgkmcnt(1)
	v_mfma_f32_32x32x16_bf16 v[2:17], v[74:77], v[54:57], v[2:17]
	v_cvt_pk_bf16_f32 v50, v102, v103
	v_cvt_pk_bf16_f32 v51, v104, v105
	v_cvt_pk_bf16_f32 v52, v106, v107
	v_cvt_pk_bf16_f32 v53, v108, v109
	v_add_f32_e32 v110, v110, v203
	v_add_f32_e32 v110, v110, v204
	v_add_f32_e32 v110, v110, v205
	v_add_f32_e32 v110, v110, v206
	s_nop 0
	v_mfma_f32_32x32x16_bf16 v[18:33], v[70:73], v[50:53], v[18:33]
	v_add_f32_e32 v110, v110, v102
	v_add_f32_e32 v110, v110, v103
	v_add_f32_e32 v110, v110, v104
	v_add_f32_e32 v110, v110, v105
	s_waitcnt lgkmcnt(0)
	v_mfma_f32_32x32x16_bf16 v[2:17], v[78:81], v[50:53], v[2:17]
	v_add_f32_e32 v110, v110, v106
	v_add_f32_e32 v110, v110, v107
	v_add_f32_e32 v110, v110, v108
	v_add_f32_e32 v110, v110, v109
	s_setprio 2
	s_waitcnt lgkmcnt(0)
	s_barrier
	ds_read_b128 v[240:243], v165
	ds_read_b128 v[244:247], v165 offset:4608
	ds_read_b128 v[102:105], v165 offset:32
	ds_read_b128 v[106:109], v165 offset:4640
	v_add_f32_e32 v1, v1, v213
	v_exp_f32_e32 v185, v130
	v_exp_f32_e32 v186, v131
	v_exp_f32_e32 v187, v132
	v_exp_f32_e32 v194, v133
	v_exp_f32_e32 v195, v134
	v_exp_f32_e32 v196, v135
	v_exp_f32_e32 v197, v136
	v_exp_f32_e32 v198, v137
	s_waitcnt lgkmcnt(2)
	v_mfma_f32_32x32x16_bf16 v[66:81], v[240:243], v[158:161], v[34:49]
	v_mfma_f32_32x32x16_bf16 v[50:65], v[244:247], v[158:161], v[34:49]
	v_exp_f32_e32 v134, v138
	v_exp_f32_e32 v135, v139
	v_exp_f32_e32 v136, v140
	v_exp_f32_e32 v137, v141
	v_exp_f32_e32 v138, v142
	v_exp_f32_e32 v139, v143
	v_exp_f32_e32 v140, v144
	v_exp_f32_e32 v141, v145
	s_waitcnt lgkmcnt(1)
	v_mfma_f32_32x32x16_bf16 v[66:81], v[102:105], v[154:157], v[66:81]
	v_exp_f32_e32 v142, v82
	v_exp_f32_e32 v143, v83
	v_exp_f32_e32 v144, v84
	v_exp_f32_e32 v145, v85
	v_exp_f32_e32 v199, v86
	v_exp_f32_e32 v200, v87
	v_exp_f32_e32 v201, v88
	v_exp_f32_e32 v202, v89
	s_waitcnt lgkmcnt(0)
	v_mfma_f32_32x32x16_bf16 v[50:65], v[106:109], v[154:157], v[50:65]
	v_exp_f32_e32 v203, v90
	v_exp_f32_e32 v204, v91
	v_exp_f32_e32 v205, v92
	v_exp_f32_e32 v206, v93
	v_exp_f32_e32 v207, v94
	v_exp_f32_e32 v208, v95
	v_exp_f32_e32 v209, v96
	v_exp_f32_e32 v210, v97
	v_add_f32_e32 v1, v1, v110
	v_add_u32_e32 v111, s26, v163
	ds_read_b128 v[240:243], v165 offset:9216
	ds_read_b128 v[244:247], v165 offset:13824
	ds_read_b128 v[82:85], v111 offset:41472
	ds_read_b128 v[86:89], v111 offset:36864
	ds_read_b128 v[90:93], v111 offset:36896
	ds_read_b128 v[94:97], v111 offset:41504
	ds_read_b128 v[98:101], v111 offset:36928
	ds_read_b128 v[102:105], v111 offset:41536
	ds_read_b128 v[106:109], v111 offset:36960
	ds_read_b128 v[110:113], v111 offset:41568
	s_cmp_gt_i32 s24, 2
	s_cselect_b32 s27, -3, 2
	s_add_i32 s27, s27, s24
	s_mulk_i32 s27, 0x2400
	v_add_u32_e32 v250, s27, v182
	s_mov_b32 s27, 0x18950000
	s_waitcnt vmcnt(3)
	ds_write_b128 v182, v[146:149] offset:18432
	s_waitcnt vmcnt(2)
	ds_write_b128 v250, v[150:153] offset:36864
	s_add_i32 s92, s23, -4
	s_lshl_b32 s92, s92, 13
	s_add_u32 vcc_lo, s100, s92
	s_addc_u32 vcc_hi, s101, 0
	global_load_dwordx4 v[126:129], v248, vcc
	s_lshl_b32 s92, s25, 7
	s_add_u32 vcc_lo, s98, s92
	s_addc_u32 vcc_hi, s99, 0
	global_load_dwordx4 v[122:125], v249, vcc
	s_add_i32 s26, s24, 1
	s_setprio 1
	v_cvt_pk_bf16_f32 v130, v185, v186
	v_cvt_pk_bf16_f32 v131, v187, v194
	v_cvt_pk_bf16_f32 v132, v195, v196
	v_cvt_pk_bf16_f32 v133, v197, v198
	s_waitcnt lgkmcnt(8)
	s_nop 0
	v_mfma_f32_32x32x16_bf16 v[18:33], v[86:89], v[130:133], v[18:33]
	v_add_f32_e32 v146, v185, v186
	v_add_f32_e32 v146, v146, v187
	v_add_f32_e32 v146, v146, v194
	s_nop 0
	v_mfma_f32_32x32x16_bf16 v[2:17], v[82:85], v[130:133], v[2:17]
	v_cvt_pk_bf16_f32 v86, v134, v135
	v_cvt_pk_bf16_f32 v87, v136, v137
	v_cvt_pk_bf16_f32 v88, v138, v139
	v_cvt_pk_bf16_f32 v89, v140, v141
	v_add_f32_e32 v146, v146, v195
	v_add_f32_e32 v146, v146, v196
	v_add_f32_e32 v146, v146, v197
	v_add_f32_e32 v146, v146, v198
	s_waitcnt lgkmcnt(7)
	v_mfma_f32_32x32x16_bf16 v[18:33], v[90:93], v[86:89], v[18:33]
	v_add_f32_e32 v146, v146, v134
	v_add_f32_e32 v146, v146, v135
	v_add_f32_e32 v146, v146, v136
	v_add_f32_e32 v146, v146, v137
	s_waitcnt lgkmcnt(6)
	v_mfma_f32_32x32x16_bf16 v[2:17], v[94:97], v[86:89], v[2:17]
	v_cvt_pk_bf16_f32 v82, v142, v143
	v_cvt_pk_bf16_f32 v83, v144, v145
	v_cvt_pk_bf16_f32 v84, v199, v200
	v_cvt_pk_bf16_f32 v85, v201, v202
	v_add_f32_e32 v146, v146, v138
	v_add_f32_e32 v146, v146, v139
	v_add_f32_e32 v146, v146, v140
	v_add_f32_e32 v146, v146, v141
	s_waitcnt lgkmcnt(5)
	v_mfma_f32_32x32x16_bf16 v[18:33], v[98:101], v[82:85], v[18:33]
	v_add_f32_e32 v146, v146, v142
	v_add_f32_e32 v146, v146, v143
	v_add_f32_e32 v146, v146, v144
	v_add_f32_e32 v146, v146, v145
	s_waitcnt lgkmcnt(4)
	v_mfma_f32_32x32x16_bf16 v[2:17], v[102:105], v[82:85], v[2:17]
	v_cvt_pk_bf16_f32 v86, v203, v204
	v_cvt_pk_bf16_f32 v87, v205, v206
	v_cvt_pk_bf16_f32 v88, v207, v208
	v_cvt_pk_bf16_f32 v89, v209, v210
	v_add_f32_e32 v146, v146, v199
	v_add_f32_e32 v146, v146, v200
	v_add_f32_e32 v146, v146, v201
	v_add_f32_e32 v146, v146, v202
	s_waitcnt lgkmcnt(3)
	v_mfma_f32_32x32x16_bf16 v[18:33], v[106:109], v[86:89], v[18:33]
	v_add_f32_e32 v146, v146, v203
	v_add_f32_e32 v146, v146, v204
	v_add_f32_e32 v146, v146, v205
	v_add_f32_e32 v146, v146, v206
	s_waitcnt lgkmcnt(2)
	v_mfma_f32_32x32x16_bf16 v[2:17], v[110:113], v[86:89], v[2:17]
	v_add_f32_e32 v146, v146, v207
	v_add_f32_e32 v146, v146, v208
	v_add_f32_e32 v146, v146, v209
	v_add_f32_e32 v146, v146, v210
	s_setprio 0
	ds_read_b128 v[130:133], v165 offset:9248
	ds_read_b128 v[138:141], v165 offset:13856
	s_cmp_lg_u32 s24, 4
	s_cselect_b32 s24, s26, 0
	s_waitcnt lgkmcnt(2)
	v_mfma_f32_32x32x16_bf16 v[98:113], v[240:243], v[158:161], v[34:49]
	v_exp_f32_e32 v142, v66
	v_exp_f32_e32 v143, v67
	v_exp_f32_e32 v144, v68
	v_exp_f32_e32 v145, v69
	v_exp_f32_e32 v147, v70
	v_exp_f32_e32 v148, v71
	v_exp_f32_e32 v149, v72
	v_exp_f32_e32 v150, v73
	s_waitcnt lgkmcnt(1)
	v_mfma_f32_32x32x16_bf16 v[82:97], v[244:247], v[158:161], v[34:49]
	v_exp_f32_e32 v151, v74
	v_exp_f32_e32 v152, v75
	v_exp_f32_e32 v153, v76
	v_exp_f32_e32 v178, v77
	v_exp_f32_e32 v134, v78
	v_exp_f32_e32 v135, v79
	v_exp_f32_e32 v136, v80
	v_exp_f32_e32 v137, v81
	v_mfma_f32_32x32x16_bf16 v[98:113], v[130:133], v[154:157], v[98:113]
	v_exp_f32_e32 v179, v50
	v_exp_f32_e32 v185, v51
	v_exp_f32_e32 v186, v52
	v_exp_f32_e32 v187, v53
	v_exp_f32_e32 v194, v54
	v_exp_f32_e32 v195, v55
	v_exp_f32_e32 v196, v56
	v_exp_f32_e32 v197, v57
	s_waitcnt lgkmcnt(0)
	v_mfma_f32_32x32x16_bf16 v[82:97], v[138:141], v[154:157], v[82:97]
	v_exp_f32_e32 v198, v58
	v_exp_f32_e32 v199, v59
	v_exp_f32_e32 v200, v60
	v_exp_f32_e32 v201, v61
	v_exp_f32_e32 v138, v62
	v_exp_f32_e32 v139, v63
	v_exp_f32_e32 v140, v64
	v_exp_f32_e32 v141, v65
	s_cmp_gt_i32 s24, 2
	s_cselect_b32 s25, -3, 2
	s_add_i32 s25, s25, s24
	s_mulk_i32 s25, 0x2400
	v_add_u32_e32 v50, s25, v182
	s_add_i32 s25, s24, 1
	s_cmp_lg_u32 s24, 4
	s_cselect_b32 s25, s25, 0
	s_add_i32 s24, s23, -3
	s_min_u32 s26, s24, s13
	s_lshl_b32 s92, s26, 13
	s_waitcnt vmcnt(3)
	ds_write_b128 v182, v[118:121] offset:27648
	s_waitcnt vmcnt(2)
	ds_write_b128 v50, v[114:117] offset:36864
	s_add_u32 vcc_lo, s100, s92
	s_addc_u32 vcc_hi, s101, 0
	global_load_dwordx4 v[118:121], v248, vcc
	s_add_i32 s92, s23, -4
	s_lshl_b32 s92, s92, 7
	s_add_u32 vcc_lo, s98, s92
	s_addc_u32 vcc_hi, s99, 0
	global_load_dwordx4 v[114:117], v249, vcc
	s_mul_i32 s27, s25, 0x2400
	s_add_i32 s28, s27, 0xffffdc00
	s_cmp_lg_u32 s25, 0
	s_cselect_b32 s28, s28, 0x9000
	v_add_u32_e32 v78, s28, v163
	ds_read_b128 v[50:53], v78 offset:36864
	ds_read_b128 v[54:57], v78 offset:36896
	ds_read_b128 v[58:61], v78 offset:41472
	ds_read_b128 v[62:65], v78 offset:41504
	ds_read_b128 v[66:69], v78 offset:36928
	ds_read_b128 v[70:73], v78 offset:36960
	ds_read_b128 v[74:77], v78 offset:41536
	ds_read_b128 v[78:81], v78 offset:41568
	s_setprio 3
	v_cvt_pk_bf16_f32 v130, v142, v143
	v_cvt_pk_bf16_f32 v131, v144, v145
	v_cvt_pk_bf16_f32 v132, v147, v148
	v_cvt_pk_bf16_f32 v133, v149, v150
	s_waitcnt lgkmcnt(7)
	s_nop 0
	v_mfma_f32_32x32x16_bf16 v[18:33], v[50:53], v[130:133], v[18:33]
	v_add_f32_e32 v176, v142, v143
	v_add_f32_e32 v176, v176, v144
	v_add_f32_e32 v176, v176, v145
	s_waitcnt lgkmcnt(5)
	v_mfma_f32_32x32x16_bf16 v[2:17], v[58:61], v[130:133], v[2:17]
	v_cvt_pk_bf16_f32 v50, v151, v152
	v_cvt_pk_bf16_f32 v51, v153, v178
	v_cvt_pk_bf16_f32 v52, v134, v135
	v_cvt_pk_bf16_f32 v53, v136, v137
	v_add_f32_e32 v176, v176, v147
	v_add_f32_e32 v176, v176, v148
	v_add_f32_e32 v176, v176, v149
	v_add_f32_e32 v176, v176, v150
	s_nop 0
	v_mfma_f32_32x32x16_bf16 v[18:33], v[54:57], v[50:53], v[18:33]
	v_add_f32_e32 v176, v176, v151
	v_add_f32_e32 v176, v176, v152
	v_add_f32_e32 v176, v176, v153
	v_add_f32_e32 v176, v176, v178
	s_waitcnt lgkmcnt(4)
	v_mfma_f32_32x32x16_bf16 v[2:17], v[62:65], v[50:53], v[2:17]
	v_cvt_pk_bf16_f32 v54, v179, v185
	v_cvt_pk_bf16_f32 v55, v186, v187
	v_cvt_pk_bf16_f32 v56, v194, v195
	v_cvt_pk_bf16_f32 v57, v196, v197
	v_add_f32_e32 v176, v176, v134
	v_add_f32_e32 v176, v176, v135
	v_add_f32_e32 v176, v176, v136
	v_add_f32_e32 v176, v176, v137
	s_waitcnt lgkmcnt(3)
	v_mfma_f32_32x32x16_bf16 v[18:33], v[66:69], v[54:57], v[18:33]
	v_add_f32_e32 v176, v176, v179
	v_add_f32_e32 v176, v176, v185
	v_add_f32_e32 v176, v176, v186
	v_add_f32_e32 v176, v176, v187
	s_waitcnt lgkmcnt(1)
	v_mfma_f32_32x32x16_bf16 v[2:17], v[74:77], v[54:57], v[2:17]
	v_cvt_pk_bf16_f32 v50, v198, v199
	v_cvt_pk_bf16_f32 v51, v200, v201
	v_cvt_pk_bf16_f32 v52, v138, v139
	v_cvt_pk_bf16_f32 v53, v140, v141
	v_add_f32_e32 v176, v176, v194
	v_add_f32_e32 v176, v176, v195
	v_add_f32_e32 v176, v176, v196
	v_add_f32_e32 v176, v176, v197
	s_nop 0
	v_mfma_f32_32x32x16_bf16 v[18:33], v[70:73], v[50:53], v[18:33]
	v_add_f32_e32 v176, v176, v198
	v_add_f32_e32 v176, v176, v199
	v_add_f32_e32 v176, v176, v200
	v_add_f32_e32 v176, v176, v201
	s_waitcnt lgkmcnt(0)
	v_mfma_f32_32x32x16_bf16 v[2:17], v[78:81], v[50:53], v[2:17]
	v_add_f32_e32 v176, v176, v138
	v_add_f32_e32 v176, v176, v139
	v_add_f32_e32 v176, v176, v140
	v_add_f32_e32 v176, v176, v141
	s_setprio 2
	s_waitcnt lgkmcnt(0)
	s_barrier
	ds_read_b128 v[240:243], v165 offset:18432
	ds_read_b128 v[244:247], v165 offset:23040
	ds_read_b128 v[134:137], v165 offset:18464
	ds_read_b128 v[138:141], v165 offset:23072
	v_add_f32_e32 v1, v1, v146
	v_exp_f32_e32 v142, v98
	v_exp_f32_e32 v143, v99
	v_exp_f32_e32 v144, v100
	v_exp_f32_e32 v145, v101
	v_exp_f32_e32 v146, v102
	v_exp_f32_e32 v147, v103
	v_exp_f32_e32 v148, v104
	v_exp_f32_e32 v149, v105
	s_waitcnt lgkmcnt(2)
	v_mfma_f32_32x32x16_bf16 v[66:81], v[240:243], v[158:161], v[34:49]
	v_mfma_f32_32x32x16_bf16 v[50:65], v[244:247], v[158:161], v[34:49]
	v_exp_f32_e32 v150, v106
	v_exp_f32_e32 v151, v107
	v_exp_f32_e32 v152, v108
	v_exp_f32_e32 v153, v109
	v_exp_f32_e32 v177, v110
	v_exp_f32_e32 v178, v111
	v_exp_f32_e32 v179, v112
	v_exp_f32_e32 v185, v113
	s_waitcnt lgkmcnt(1)
	v_mfma_f32_32x32x16_bf16 v[66:81], v[134:137], v[154:157], v[66:81]
	v_exp_f32_e32 v186, v82
	v_exp_f32_e32 v187, v83
	v_exp_f32_e32 v194, v84
	v_exp_f32_e32 v195, v85
	v_exp_f32_e32 v134, v86
	v_exp_f32_e32 v135, v87
	v_exp_f32_e32 v136, v88
	v_exp_f32_e32 v137, v89
	s_waitcnt lgkmcnt(0)
	v_mfma_f32_32x32x16_bf16 v[50:65], v[138:141], v[154:157], v[50:65]
	v_exp_f32_e32 v196, v90
	v_exp_f32_e32 v197, v91
	v_exp_f32_e32 v198, v92
	v_exp_f32_e32 v199, v93
	v_exp_f32_e32 v138, v94
	v_exp_f32_e32 v139, v95
	v_exp_f32_e32 v140, v96
	v_exp_f32_e32 v141, v97
	s_cmp_gt_i32 s25, 2
	s_cselect_b32 s28, -3, 2
	s_waitcnt vmcnt(3)
	ds_write_b128 v182, v[126:129]
	s_add_i32 s28, s28, s25
	v_add_u32_e32 v126, s27, v163
	s_add_i32 s27, s23, -2
	s_mulk_i32 s28, 0x2400
	s_min_u32 s27, s27, s13
	v_add_u32_e32 v82, s28, v182
	s_lshl_b32 s92, s27, 13
	s_waitcnt vmcnt(2)
	ds_write_b128 v82, v[122:125] offset:36864
	ds_read_b128 v[240:243], v165 offset:27648
	ds_read_b128 v[244:247], v165 offset:32256
	ds_read_b128 v[82:85], v126 offset:41472
	ds_read_b128 v[86:89], v126 offset:36864
	ds_read_b128 v[90:93], v126 offset:36896
	ds_read_b128 v[94:97], v126 offset:41504
	ds_read_b128 v[106:109], v126 offset:36928
	ds_read_b128 v[110:113], v126 offset:41536
	ds_read_b128 v[122:125], v126 offset:36960
	ds_read_b128 v[126:129], v126 offset:41568
	s_add_u32 vcc_lo, s100, s92
	s_addc_u32 vcc_hi, s101, 0
	global_load_dwordx4 v[98:101], v248, vcc
	s_lshl_b32 s92, s26, 7
	s_add_u32 vcc_lo, s98, s92
	s_addc_u32 vcc_hi, s99, 0
	global_load_dwordx4 v[102:105], v249, vcc
	v_add_f32_e32 v1, v1, v176
	s_add_i32 s28, s25, 1
	s_setprio 1
	v_cvt_pk_bf16_f32 v130, v142, v143
	v_cvt_pk_bf16_f32 v131, v144, v145
	v_cvt_pk_bf16_f32 v132, v146, v147
	v_cvt_pk_bf16_f32 v133, v148, v149
	s_waitcnt lgkmcnt(6)
	s_nop 0
	v_mfma_f32_32x32x16_bf16 v[18:33], v[86:89], v[130:133], v[18:33]
	v_add_f32_e32 v176, v142, v143
	v_add_f32_e32 v176, v176, v144
	v_add_f32_e32 v176, v176, v145
	s_nop 0
	v_mfma_f32_32x32x16_bf16 v[2:17], v[82:85], v[130:133], v[2:17]
	v_cvt_pk_bf16_f32 v86, v150, v151
	v_cvt_pk_bf16_f32 v87, v152, v153
	v_cvt_pk_bf16_f32 v88, v177, v178
	v_cvt_pk_bf16_f32 v89, v179, v185
	v_add_f32_e32 v176, v176, v146
	v_add_f32_e32 v176, v176, v147
	v_add_f32_e32 v176, v176, v148
	v_add_f32_e32 v176, v176, v149
	s_waitcnt lgkmcnt(5)
	v_mfma_f32_32x32x16_bf16 v[18:33], v[90:93], v[86:89], v[18:33]
	v_add_f32_e32 v176, v176, v150
	v_add_f32_e32 v176, v176, v151
	v_add_f32_e32 v176, v176, v152
	v_add_f32_e32 v176, v176, v153
	s_waitcnt lgkmcnt(4)
	v_mfma_f32_32x32x16_bf16 v[2:17], v[94:97], v[86:89], v[2:17]
	v_cvt_pk_bf16_f32 v82, v186, v187
	v_cvt_pk_bf16_f32 v83, v194, v195
	v_cvt_pk_bf16_f32 v84, v134, v135
	v_cvt_pk_bf16_f32 v85, v136, v137
	v_add_f32_e32 v176, v176, v177
	v_add_f32_e32 v176, v176, v178
	v_add_f32_e32 v176, v176, v179
	v_add_f32_e32 v176, v176, v185
	s_waitcnt lgkmcnt(3)
	v_mfma_f32_32x32x16_bf16 v[18:33], v[106:109], v[82:85], v[18:33]
	v_add_f32_e32 v176, v176, v186
	v_add_f32_e32 v176, v176, v187
	v_add_f32_e32 v176, v176, v194
	v_add_f32_e32 v176, v176, v195
	s_waitcnt lgkmcnt(2)
	v_mfma_f32_32x32x16_bf16 v[2:17], v[110:113], v[82:85], v[2:17]
	v_cvt_pk_bf16_f32 v86, v196, v197
	v_cvt_pk_bf16_f32 v87, v198, v199
	v_cvt_pk_bf16_f32 v88, v138, v139
	v_cvt_pk_bf16_f32 v89, v140, v141
	v_add_f32_e32 v176, v176, v134
	v_add_f32_e32 v176, v176, v135
	v_add_f32_e32 v176, v176, v136
	v_add_f32_e32 v176, v176, v137
	s_waitcnt lgkmcnt(1)
	v_mfma_f32_32x32x16_bf16 v[18:33], v[122:125], v[86:89], v[18:33]
	v_add_f32_e32 v176, v176, v196
	v_add_f32_e32 v176, v176, v197
	v_add_f32_e32 v176, v176, v198
	v_add_f32_e32 v176, v176, v199
	s_waitcnt lgkmcnt(0)
	v_mfma_f32_32x32x16_bf16 v[2:17], v[126:129], v[86:89], v[2:17]
	v_add_f32_e32 v176, v176, v138
	v_add_f32_e32 v176, v176, v139
	v_add_f32_e32 v176, v176, v140
	v_add_f32_e32 v176, v176, v141
	s_setprio 0
	ds_read_b128 v[106:109], v165 offset:27680
	ds_read_b128 v[122:125], v165 offset:32288
	s_cmp_lg_u32 s25, 4
	s_cselect_b32 s25, s28, 0
	s_waitcnt lgkmcnt(2)
	v_mfma_f32_32x32x16_bf16 v[138:153], v[240:243], v[158:161], v[34:49]
	v_exp_f32_e32 v126, v66
	v_exp_f32_e32 v127, v67
	v_exp_f32_e32 v128, v68
	v_exp_f32_e32 v129, v69
	v_exp_f32_e32 v130, v70
	v_exp_f32_e32 v131, v71
	v_exp_f32_e32 v132, v72
	v_exp_f32_e32 v133, v73
	s_waitcnt lgkmcnt(1)
	v_mfma_f32_32x32x16_bf16 v[82:97], v[244:247], v[158:161], v[34:49]
	v_exp_f32_e32 v134, v74
	v_exp_f32_e32 v135, v75
	v_exp_f32_e32 v136, v76
	v_exp_f32_e32 v137, v77
	v_exp_f32_e32 v177, v78
	v_exp_f32_e32 v178, v79
	v_exp_f32_e32 v179, v80
	v_exp_f32_e32 v185, v81
	v_mfma_f32_32x32x16_bf16 v[138:153], v[106:109], v[154:157], v[138:153]
	v_exp_f32_e32 v80, v50
	v_exp_f32_e32 v81, v51
	v_exp_f32_e32 v186, v52
	v_exp_f32_e32 v187, v53
	v_exp_f32_e32 v194, v54
	v_exp_f32_e32 v195, v55
	v_exp_f32_e32 v196, v56
	v_exp_f32_e32 v197, v57
	s_waitcnt lgkmcnt(0)
	v_mfma_f32_32x32x16_bf16 v[82:97], v[122:125], v[154:157], v[82:97]
	v_exp_f32_e32 v198, v58
	v_exp_f32_e32 v199, v59
	v_exp_f32_e32 v200, v60
	v_exp_f32_e32 v201, v61
	v_exp_f32_e32 v122, v62
	v_exp_f32_e32 v123, v63
	v_exp_f32_e32 v124, v64
	v_exp_f32_e32 v125, v65
	s_cmp_gt_i32 s25, 2
	s_cselect_b32 s26, -3, 2
	s_add_i32 s26, s26, s25
	s_mulk_i32 s26, 0x2400
	v_add_u32_e32 v50, s26, v182
	s_add_i32 s26, s25, 1
	s_cmp_lg_u32 s25, 4
	s_cselect_b32 s25, s26, 0
	s_add_i32 s26, s23, -1
	s_min_u32 s26, s26, s13
	s_lshl_b32 s92, s26, 13
	s_waitcnt vmcnt(3)
	ds_write_b128 v182, v[118:121] offset:9216
	s_waitcnt vmcnt(2)
	ds_write_b128 v50, v[114:117] offset:36864
	s_add_u32 vcc_lo, s100, s92
	s_addc_u32 vcc_hi, s101, 0
	global_load_dwordx4 v[56:59], v248, vcc
	s_lshl_b32 s92, s27, 7
	s_add_u32 vcc_lo, s98, s92
	s_addc_u32 vcc_hi, s99, 0
	global_load_dwordx4 v[52:55], v249, vcc
	s_nop 0
	s_mul_i32 s27, s25, 0x2400
	s_add_i32 s28, s27, 0xffffdc00
	s_cmp_lg_u32 s25, 0
	s_cselect_b32 s28, s28, 0x9000
	v_add_u32_e32 v50, s28, v163
	ds_read_b128 v[60:63], v50 offset:36864
	ds_read_b128 v[64:67], v50 offset:36896
	ds_read_b128 v[68:71], v50 offset:41472
	ds_read_b128 v[72:75], v50 offset:41504
	ds_read_b128 v[76:79], v50 offset:36928
	ds_read_b128 v[106:109], v50 offset:36960
	ds_read_b128 v[110:113], v50 offset:41536
	ds_read_b128 v[114:117], v50 offset:41568
	s_setprio 3
	v_cvt_pk_bf16_f32 v118, v126, v127
	v_cvt_pk_bf16_f32 v119, v128, v129
	v_cvt_pk_bf16_f32 v120, v130, v131
	v_cvt_pk_bf16_f32 v121, v132, v133
	s_waitcnt lgkmcnt(7)
	s_nop 0
	v_mfma_f32_32x32x16_bf16 v[18:33], v[60:63], v[118:121], v[18:33]
	v_add_f32_e32 v50, v126, v127
	v_add_f32_e32 v50, v50, v128
	v_add_f32_e32 v50, v50, v129
	s_waitcnt lgkmcnt(5)
	v_mfma_f32_32x32x16_bf16 v[2:17], v[68:71], v[118:121], v[2:17]
	v_cvt_pk_bf16_f32 v60, v134, v135
	v_cvt_pk_bf16_f32 v61, v136, v137
	v_cvt_pk_bf16_f32 v62, v177, v178
	v_cvt_pk_bf16_f32 v63, v179, v185
	v_add_f32_e32 v50, v50, v130
	v_add_f32_e32 v50, v50, v131
	v_add_f32_e32 v50, v50, v132
	v_add_f32_e32 v50, v50, v133
	s_nop 0
	v_mfma_f32_32x32x16_bf16 v[18:33], v[64:67], v[60:63], v[18:33]
	v_add_f32_e32 v50, v50, v134
	v_add_f32_e32 v50, v50, v135
	v_add_f32_e32 v50, v50, v136
	v_add_f32_e32 v50, v50, v137
	s_waitcnt lgkmcnt(4)
	v_mfma_f32_32x32x16_bf16 v[2:17], v[72:75], v[60:63], v[2:17]
	v_cvt_pk_bf16_f32 v64, v80, v81
	v_cvt_pk_bf16_f32 v65, v186, v187
	v_cvt_pk_bf16_f32 v66, v194, v195
	v_cvt_pk_bf16_f32 v67, v196, v197
	v_add_f32_e32 v50, v50, v177
	v_add_f32_e32 v50, v50, v178
	v_add_f32_e32 v50, v50, v179
	v_add_f32_e32 v50, v50, v185
	s_waitcnt lgkmcnt(3)
	v_mfma_f32_32x32x16_bf16 v[18:33], v[76:79], v[64:67], v[18:33]
	v_add_f32_e32 v50, v50, v80
	v_add_f32_e32 v50, v50, v81
	v_add_f32_e32 v50, v50, v186
	v_add_f32_e32 v50, v50, v187
	s_waitcnt lgkmcnt(1)
	v_mfma_f32_32x32x16_bf16 v[2:17], v[110:113], v[64:67], v[2:17]
	v_cvt_pk_bf16_f32 v60, v198, v199
	v_cvt_pk_bf16_f32 v61, v200, v201
	v_cvt_pk_bf16_f32 v62, v122, v123
	v_cvt_pk_bf16_f32 v63, v124, v125
	v_add_f32_e32 v50, v50, v194
	v_add_f32_e32 v50, v50, v195
	v_add_f32_e32 v50, v50, v196
	v_add_f32_e32 v50, v50, v197
	s_nop 0
	v_mfma_f32_32x32x16_bf16 v[18:33], v[106:109], v[60:63], v[18:33]
	v_add_f32_e32 v50, v50, v198
	v_add_f32_e32 v50, v50, v199
	v_add_f32_e32 v50, v50, v200
	v_add_f32_e32 v50, v50, v201
	s_waitcnt lgkmcnt(0)
	v_mfma_f32_32x32x16_bf16 v[2:17], v[114:117], v[60:63], v[2:17]
	v_add_f32_e32 v50, v50, v122
	v_add_f32_e32 v50, v50, v123
	v_add_f32_e32 v50, v50, v124
	v_add_f32_e32 v50, v50, v125
	s_setprio 2
	s_waitcnt lgkmcnt(0)
	s_barrier
	ds_read_b128 v[240:243], v165
	ds_read_b128 v[244:247], v165 offset:4608
	ds_read_b128 v[68:71], v165 offset:32
	ds_read_b128 v[72:75], v165 offset:4640
	v_add_f32_e32 v1, v1, v176
	v_exp_f32_e32 v176, v138
	v_exp_f32_e32 v177, v139
	v_exp_f32_e32 v178, v140
	v_exp_f32_e32 v179, v141
	v_exp_f32_e32 v185, v142
	v_exp_f32_e32 v186, v143
	v_exp_f32_e32 v187, v144
	v_exp_f32_e32 v194, v145
	s_waitcnt lgkmcnt(2)
	v_mfma_f32_32x32x16_bf16 v[122:137], v[240:243], v[158:161], v[34:49]
	v_mfma_f32_32x32x16_bf16 v[106:121], v[244:247], v[158:161], v[34:49]
	v_exp_f32_e32 v195, v146
	v_exp_f32_e32 v196, v147
	v_exp_f32_e32 v197, v148
	v_exp_f32_e32 v198, v149
	v_exp_f32_e32 v146, v150
	v_exp_f32_e32 v147, v151
	v_exp_f32_e32 v148, v152
	v_exp_f32_e32 v149, v153
	s_waitcnt lgkmcnt(1)
	v_mfma_f32_32x32x16_bf16 v[122:137], v[68:71], v[154:157], v[122:137]
	v_exp_f32_e32 v150, v82
	v_exp_f32_e32 v151, v83
	v_exp_f32_e32 v152, v84
	v_exp_f32_e32 v153, v85
	v_exp_f32_e32 v199, v86
	v_exp_f32_e32 v200, v87
	v_exp_f32_e32 v201, v88
	v_exp_f32_e32 v202, v89
	s_waitcnt lgkmcnt(0)
	v_mfma_f32_32x32x16_bf16 v[106:121], v[72:75], v[154:157], v[106:121]
	v_exp_f32_e32 v203, v90
	v_exp_f32_e32 v204, v91
	v_exp_f32_e32 v205, v92
	v_exp_f32_e32 v206, v93
	v_exp_f32_e32 v207, v94
	v_exp_f32_e32 v208, v95
	v_exp_f32_e32 v209, v96
	v_exp_f32_e32 v210, v97
	v_add_u32_e32 v88, s27, v163
	ds_read_b128 v[240:243], v165 offset:9216
	ds_read_b128 v[244:247], v165 offset:13824
	ds_read_b128 v[60:63], v88 offset:41472
	ds_read_b128 v[64:67], v88 offset:36864
	ds_read_b128 v[68:71], v88 offset:36896
	ds_read_b128 v[72:75], v88 offset:41504
	ds_read_b128 v[76:79], v88 offset:36928
	ds_read_b128 v[80:83], v88 offset:41536
	ds_read_b128 v[84:87], v88 offset:36960
	ds_read_b128 v[88:91], v88 offset:41568
	s_cmp_gt_i32 s25, 2
	s_cselect_b32 s28, -3, 2
	s_add_i32 s28, s28, s25
	s_mulk_i32 s28, 0x2400
	s_min_u32 s27, s23, s13
	v_add_u32_e32 v51, s28, v182
	s_lshl_b32 s92, s27, 13
	s_waitcnt vmcnt(3)
	ds_write_b128 v182, v[98:101] offset:18432
	s_waitcnt vmcnt(2)
	ds_write_b128 v51, v[102:105] offset:36864
	v_add_f32_e32 v1, v1, v50
	s_add_u32 vcc_lo, s100, s92
	s_addc_u32 vcc_hi, s101, 0
	global_load_dwordx4 v[138:141], v248, vcc
	s_lshl_b32 s92, s26, 7
	s_add_u32 vcc_lo, s98, s92
	s_addc_u32 vcc_hi, s99, 0
	global_load_dwordx4 v[142:145], v249, vcc
	s_setprio 1
	v_mov_b32_e32 v51, v122
	v_cvt_pk_bf16_f32 v92, v176, v177
	v_cvt_pk_bf16_f32 v93, v178, v179
	v_cvt_pk_bf16_f32 v94, v185, v186
	v_cvt_pk_bf16_f32 v95, v187, v194
	s_waitcnt lgkmcnt(8)
	s_nop 0
	v_mfma_f32_32x32x16_bf16 v[18:33], v[64:67], v[92:95], v[18:33]
	v_max3_f32 v51, v51, v123, v124
	v_max3_f32 v51, v51, v125, v126
	v_add_f32_e32 v50, v176, v177
	v_add_f32_e32 v50, v50, v178
	v_add_f32_e32 v50, v50, v179
	s_nop 0
	v_mfma_f32_32x32x16_bf16 v[2:17], v[60:63], v[92:95], v[2:17]
	v_cvt_pk_bf16_f32 v64, v195, v196
	v_cvt_pk_bf16_f32 v65, v197, v198
	v_cvt_pk_bf16_f32 v66, v146, v147
	v_cvt_pk_bf16_f32 v67, v148, v149
	v_max3_f32 v51, v51, v127, v128
	v_max3_f32 v51, v51, v129, v130
	v_add_f32_e32 v50, v50, v185
	v_add_f32_e32 v50, v50, v186
	v_add_f32_e32 v50, v50, v187
	v_add_f32_e32 v50, v50, v194
	s_waitcnt lgkmcnt(7)
	v_mfma_f32_32x32x16_bf16 v[18:33], v[68:71], v[64:67], v[18:33]
	v_max3_f32 v51, v51, v131, v132
	v_max3_f32 v51, v51, v133, v134
	v_add_f32_e32 v50, v50, v195
	v_add_f32_e32 v50, v50, v196
	v_add_f32_e32 v50, v50, v197
	v_add_f32_e32 v50, v50, v198
	s_waitcnt lgkmcnt(6)
	v_mfma_f32_32x32x16_bf16 v[2:17], v[72:75], v[64:67], v[2:17]
	v_cvt_pk_bf16_f32 v60, v150, v151
	v_cvt_pk_bf16_f32 v61, v152, v153
	v_cvt_pk_bf16_f32 v62, v199, v200
	v_cvt_pk_bf16_f32 v63, v201, v202
	v_max3_f32 v51, v51, v135, v136
	v_max3_f32 v51, v51, v137, v106
	v_add_f32_e32 v50, v50, v146
	v_add_f32_e32 v50, v50, v147
	v_add_f32_e32 v50, v50, v148
	v_add_f32_e32 v50, v50, v149
	s_waitcnt lgkmcnt(5)
	v_mfma_f32_32x32x16_bf16 v[18:33], v[76:79], v[60:63], v[18:33]
	v_max3_f32 v51, v51, v107, v108
	v_max3_f32 v51, v51, v109, v110
	v_add_f32_e32 v50, v50, v150
	v_add_f32_e32 v50, v50, v151
	v_add_f32_e32 v50, v50, v152
	v_add_f32_e32 v50, v50, v153
	s_waitcnt lgkmcnt(4)
	v_mfma_f32_32x32x16_bf16 v[2:17], v[80:83], v[60:63], v[2:17]
	v_cvt_pk_bf16_f32 v64, v203, v204
	v_cvt_pk_bf16_f32 v65, v205, v206
	v_cvt_pk_bf16_f32 v66, v207, v208
	v_cvt_pk_bf16_f32 v67, v209, v210
	v_max3_f32 v51, v51, v111, v112
	v_max3_f32 v51, v51, v113, v114
	v_add_f32_e32 v50, v50, v199
	v_add_f32_e32 v50, v50, v200
	v_add_f32_e32 v50, v50, v201
	v_add_f32_e32 v50, v50, v202
	s_waitcnt lgkmcnt(3)
	v_mfma_f32_32x32x16_bf16 v[18:33], v[84:87], v[64:67], v[18:33]
	v_max3_f32 v51, v51, v115, v116
	v_max3_f32 v51, v51, v117, v118
	v_add_f32_e32 v50, v50, v203
	v_add_f32_e32 v50, v50, v204
	v_add_f32_e32 v50, v50, v205
	v_add_f32_e32 v50, v50, v206
	s_waitcnt lgkmcnt(2)
	v_mfma_f32_32x32x16_bf16 v[2:17], v[88:91], v[64:67], v[2:17]
	v_max3_f32 v51, v51, v119, v120
	v_max3_f32 v51, v51, v121, v121
	v_add_f32_e32 v50, v50, v207
	v_add_f32_e32 v50, v50, v208
	v_add_f32_e32 v50, v50, v209
	v_add_f32_e32 v50, v50, v210
	s_setprio 0
	ds_read_b128 v[146:149], v165 offset:9248
	ds_read_b128 v[60:63], v165 offset:13856
	v_add_f32_e32 v50, v1, v50
	v_mov_b32_e32 v1, v51
	s_nop 1
	v_permlane32_swap_b32_e32 v51, v1
	v_max_f32_e32 v1, v1, v1
	v_max_f32_e32 v51, v51, v51
	v_max_f32_e32 v1, v51, v1
	v_cmp_lt_f32_e32 vcc, s52, v1
	s_cbranch_vccz .LBB0_643
	v_max_f32_e32 v1, v1, v1
	v_max_f32_e32 v68, 0, v1
	v_add_f32_e32 v183, v183, v68
	v_xor_b32_e32 v34, 0x80000000, v183
	v_pk_add_f32 v[122:123], v[122:123], v[68:69] op_sel_hi:[1,0] neg_lo:[0,1] neg_hi:[0,1]
	v_pk_add_f32 v[106:107], v[106:107], v[68:69] op_sel_hi:[1,0] neg_lo:[0,1] neg_hi:[0,1]
	v_pk_add_f32 v[124:125], v[124:125], v[68:69] op_sel_hi:[1,0] neg_lo:[0,1] neg_hi:[0,1]
	v_pk_add_f32 v[108:109], v[108:109], v[68:69] op_sel_hi:[1,0] neg_lo:[0,1] neg_hi:[0,1]
	v_pk_add_f32 v[126:127], v[126:127], v[68:69] op_sel_hi:[1,0] neg_lo:[0,1] neg_hi:[0,1]
	v_pk_add_f32 v[110:111], v[110:111], v[68:69] op_sel_hi:[1,0] neg_lo:[0,1] neg_hi:[0,1]
	v_pk_add_f32 v[128:129], v[128:129], v[68:69] op_sel_hi:[1,0] neg_lo:[0,1] neg_hi:[0,1]
	v_pk_add_f32 v[112:113], v[112:113], v[68:69] op_sel_hi:[1,0] neg_lo:[0,1] neg_hi:[0,1]
	v_pk_add_f32 v[130:131], v[130:131], v[68:69] op_sel_hi:[1,0] neg_lo:[0,1] neg_hi:[0,1]
	v_pk_add_f32 v[114:115], v[114:115], v[68:69] op_sel_hi:[1,0] neg_lo:[0,1] neg_hi:[0,1]
	v_pk_add_f32 v[132:133], v[132:133], v[68:69] op_sel_hi:[1,0] neg_lo:[0,1] neg_hi:[0,1]
	v_pk_add_f32 v[116:117], v[116:117], v[68:69] op_sel_hi:[1,0] neg_lo:[0,1] neg_hi:[0,1]
	v_pk_add_f32 v[134:135], v[134:135], v[68:69] op_sel_hi:[1,0] neg_lo:[0,1] neg_hi:[0,1]
	v_pk_add_f32 v[118:119], v[118:119], v[68:69] op_sel_hi:[1,0] neg_lo:[0,1] neg_hi:[0,1]
	v_pk_add_f32 v[136:137], v[136:137], v[68:69] op_sel_hi:[1,0] neg_lo:[0,1] neg_hi:[0,1]
	v_pk_add_f32 v[120:121], v[120:121], v[68:69] op_sel_hi:[1,0] neg_lo:[0,1] neg_hi:[0,1]
	v_exp_f32_e64 v68, -v68
	v_mov_b32_e32 v35, v34
	v_mov_b32_e32 v36, v34
	v_mov_b32_e32 v37, v34
	v_mov_b32_e32 v38, v34
	v_mov_b32_e32 v39, v34
	v_mov_b32_e32 v40, v34
	v_mov_b32_e32 v41, v34
	v_mov_b32_e32 v42, v34
	v_mov_b32_e32 v43, v34
	v_mov_b32_e32 v44, v34
	v_mov_b32_e32 v45, v34
	v_mov_b32_e32 v46, v34
	v_mov_b32_e32 v47, v34
	v_mov_b32_e32 v48, v34
	v_mov_b32_e32 v49, v34
	s_nop 11
	v_pk_mul_f32 v[32:33], v[32:33], v[68:69] op_sel_hi:[1,0]
	v_pk_mul_f32 v[30:31], v[30:31], v[68:69] op_sel_hi:[1,0]
	v_pk_mul_f32 v[28:29], v[28:29], v[68:69] op_sel_hi:[1,0]
	v_pk_mul_f32 v[26:27], v[26:27], v[68:69] op_sel_hi:[1,0]
	v_pk_mul_f32 v[24:25], v[24:25], v[68:69] op_sel_hi:[1,0]
	v_pk_mul_f32 v[22:23], v[22:23], v[68:69] op_sel_hi:[1,0]
	v_pk_mul_f32 v[20:21], v[20:21], v[68:69] op_sel_hi:[1,0]
	v_pk_mul_f32 v[18:19], v[18:19], v[68:69] op_sel_hi:[1,0]
	v_pk_mul_f32 v[16:17], v[16:17], v[68:69] op_sel_hi:[1,0]
	v_pk_mul_f32 v[14:15], v[14:15], v[68:69] op_sel_hi:[1,0]
	v_pk_mul_f32 v[12:13], v[12:13], v[68:69] op_sel_hi:[1,0]
	v_pk_mul_f32 v[10:11], v[10:11], v[68:69] op_sel_hi:[1,0]
	v_pk_mul_f32 v[8:9], v[8:9], v[68:69] op_sel_hi:[1,0]
	v_pk_mul_f32 v[6:7], v[6:7], v[68:69] op_sel_hi:[1,0]
	v_pk_mul_f32 v[4:5], v[4:5], v[68:69] op_sel_hi:[1,0]
	v_pk_mul_f32 v[2:3], v[2:3], v[68:69] op_sel_hi:[1,0]
	v_mul_f32_e32 v50, v50, v68

.LBB0_661:
	s_add_i32 s26, s13, -7
	s_lshl_b32 s92, s26, 13
	s_add_u32 vcc_lo, s100, s92
	s_addc_u32 vcc_hi, s101, 0
	global_load_dwordx4 v[2:5], v248, vcc
	s_add_i32 s26, s13, -8
	s_lshl_b32 s92, s26, 7
	s_add_u32 vcc_lo, s98, s92
	s_addc_u32 vcc_hi, s99, 0
	global_load_dwordx4 v[6:9], v249, vcc
	s_mul_i32 s28, s27, 0x2400
	s_add_i32 s26, s13, -7
	s_add_i32 s29, s28, 0xffffdc00
	s_cmp_lg_u32 s27, 0
	s_cselect_b32 s29, s29, 0x9000
	v_add_u32_e32 v1, s29, v195
	ds_read_b128 v[10:13], v1 offset:36864
	ds_read_b128 v[66:69], v1 offset:36896
	ds_read_b128 v[70:73], v1 offset:41472
	ds_read_b128 v[74:77], v1 offset:41504
	ds_read_b128 v[128:131], v1 offset:36928
	ds_read_b128 v[132:135], v1 offset:36960
	ds_read_b128 v[148:151], v1 offset:41536
	ds_read_b128 v[160:163], v1 offset:41568
	s_setprio 3
	v_cvt_pk_bf16_f32 v210, v116, v117
	v_cvt_pk_bf16_f32 v211, v118, v119
	v_cvt_pk_bf16_f32 v212, v112, v113
	v_cvt_pk_bf16_f32 v213, v114, v115
	s_waitcnt lgkmcnt(7)
	s_nop 0
	v_mfma_f32_32x32x16_bf16 v[16:31], v[10:13], v[210:213], v[16:31]
	v_add_f32_e32 v1, v116, v117
	v_add_f32_e32 v1, v1, v118
	v_add_f32_e32 v1, v1, v119
	s_waitcnt lgkmcnt(5)
	v_mfma_f32_32x32x16_bf16 v[32:47], v[70:73], v[210:213], v[32:47]
	v_cvt_pk_bf16_f32 v10, v187, v186
	v_cvt_pk_bf16_f32 v11, v185, v184
	v_cvt_pk_bf16_f32 v12, v147, v146
	v_cvt_pk_bf16_f32 v13, v145, v144
	v_add_f32_e32 v1, v1, v112
	v_add_f32_e32 v1, v1, v113
	v_add_f32_e32 v1, v1, v114
	v_add_f32_e32 v1, v1, v115
	s_nop 0
	v_mfma_f32_32x32x16_bf16 v[16:31], v[66:69], v[10:13], v[16:31]
	v_add_f32_e32 v1, v1, v187
	v_add_f32_e32 v1, v1, v186
	v_add_f32_e32 v1, v1, v185
	v_add_f32_e32 v1, v1, v184
	s_waitcnt lgkmcnt(4)
	v_mfma_f32_32x32x16_bf16 v[32:47], v[74:77], v[10:13], v[32:47]
	v_cvt_pk_bf16_f32 v66, v143, v142
	v_cvt_pk_bf16_f32 v67, v141, v140
	v_cvt_pk_bf16_f32 v68, v139, v138
	v_cvt_pk_bf16_f32 v69, v137, v136
	v_add_f32_e32 v1, v1, v147
	v_add_f32_e32 v1, v1, v146
	v_add_f32_e32 v1, v1, v145
	v_add_f32_e32 v1, v1, v144
	s_waitcnt lgkmcnt(3)
	v_mfma_f32_32x32x16_bf16 v[16:31], v[128:131], v[66:69], v[16:31]
	v_add_f32_e32 v1, v1, v143
	v_add_f32_e32 v1, v1, v142
	v_add_f32_e32 v1, v1, v141
	v_add_f32_e32 v1, v1, v140
	s_waitcnt lgkmcnt(1)
	v_mfma_f32_32x32x16_bf16 v[32:47], v[148:151], v[66:69], v[32:47]
	v_cvt_pk_bf16_f32 v10, v123, v122
	v_cvt_pk_bf16_f32 v11, v121, v120
	v_cvt_pk_bf16_f32 v12, v127, v126
	v_cvt_pk_bf16_f32 v13, v125, v124
	v_add_f32_e32 v1, v1, v139
	v_add_f32_e32 v1, v1, v138
	v_add_f32_e32 v1, v1, v137
	v_add_f32_e32 v1, v1, v136
	s_nop 0
	v_mfma_f32_32x32x16_bf16 v[16:31], v[132:135], v[10:13], v[16:31]
	v_add_f32_e32 v1, v1, v123
	v_add_f32_e32 v1, v1, v122
	v_add_f32_e32 v1, v1, v121
	v_add_f32_e32 v1, v1, v120
	s_waitcnt lgkmcnt(0)
	v_mfma_f32_32x32x16_bf16 v[32:47], v[160:163], v[10:13], v[32:47]
	v_add_f32_e32 v1, v1, v127
	v_add_f32_e32 v1, v1, v126
	v_add_f32_e32 v1, v1, v125
	v_add_f32_e32 v1, v1, v124
	s_setprio 2
	s_waitcnt lgkmcnt(0)
	s_barrier
	ds_read_b128 v[240:243], v195 offset:18432
	ds_read_b128 v[244:247], v195 offset:23040
	ds_read_b128 v[66:69], v195 offset:18464
	ds_read_b128 v[74:77], v195 offset:23072
	ds_read_b128 v[144:147], v195 offset:18496
	ds_read_b128 v[148:151], v195 offset:18528
	ds_read_b128 v[160:163], v195 offset:23104
	ds_read_b128 v[184:187], v195 offset:23136
	v_exp_f32_e32 v166, v96
	v_exp_f32_e32 v167, v97
	v_exp_f32_e32 v210, v98
	v_exp_f32_e32 v211, v99
	s_waitcnt lgkmcnt(6)
	v_mfma_f32_32x32x16_bf16 v[128:143], v[240:243], v[180:183], v[48:63]
	s_waitcnt lgkmcnt(5)
	v_mfma_f32_32x32x16_bf16 v[112:127], v[244:247], v[180:183], v[48:63]
	v_exp_f32_e32 v212, v100
	v_exp_f32_e32 v213, v101
	v_exp_f32_e32 v214, v102
	v_exp_f32_e32 v215, v103
	v_mfma_f32_32x32x16_bf16 v[128:143], v[66:69], v[176:179], v[128:143]
	v_exp_f32_e32 v100, v104
	v_exp_f32_e32 v101, v105
	v_exp_f32_e32 v102, v106
	v_exp_f32_e32 v103, v107
	s_waitcnt lgkmcnt(4)
	v_mfma_f32_32x32x16_bf16 v[112:127], v[74:77], v[176:179], v[112:127]
	v_exp_f32_e32 v104, v108
	v_exp_f32_e32 v105, v109
	v_exp_f32_e32 v106, v110
	v_exp_f32_e32 v107, v111
	s_waitcnt lgkmcnt(3)
	v_mfma_f32_32x32x16_bf16 v[128:143], v[144:147], v[172:175], v[128:143]
	v_exp_f32_e32 v108, v80
	v_exp_f32_e32 v109, v81
	v_exp_f32_e32 v110, v82
	v_exp_f32_e32 v111, v83
	s_waitcnt lgkmcnt(1)
	v_mfma_f32_32x32x16_bf16 v[112:127], v[160:163], v[172:175], v[112:127]
	v_exp_f32_e32 v144, v84
	v_exp_f32_e32 v145, v85
	v_exp_f32_e32 v146, v86
	v_exp_f32_e32 v147, v87
	v_mfma_f32_32x32x16_bf16 v[128:143], v[148:151], v[168:171], v[128:143]
	v_exp_f32_e32 v216, v88
	v_exp_f32_e32 v217, v89
	v_exp_f32_e32 v218, v90
	v_exp_f32_e32 v219, v91
	s_waitcnt lgkmcnt(0)
	v_mfma_f32_32x32x16_bf16 v[112:127], v[184:187], v[168:171], v[112:127]
	v_exp_f32_e32 v148, v92
	v_exp_f32_e32 v149, v93
	v_exp_f32_e32 v150, v94
	v_exp_f32_e32 v151, v95
	v_add_f32_e32 v1, v64, v1
	v_add_u32_e32 v92, s28, v195
	ds_read_b128 v[240:243], v195 offset:27648
	ds_read_b128 v[244:247], v195 offset:32256
	ds_read_b128 v[64:67], v92 offset:41472
	ds_read_b128 v[68:71], v92 offset:36864
	ds_read_b128 v[72:75], v92 offset:36896
	ds_read_b128 v[76:79], v92 offset:41504
	ds_read_b128 v[80:83], v92 offset:36928
	ds_read_b128 v[84:87], v92 offset:41536
	ds_read_b128 v[88:91], v92 offset:36960
	ds_read_b128 v[92:95], v92 offset:41568
	s_cmp_gt_i32 s27, 2
	s_cselect_b32 s29, -3, 2
	s_add_i32 s29, s29, s27
	s_add_i32 s28, s13, -6
	s_mulk_i32 s29, 0x2400
	s_min_u32 s28, s28, s12
	v_add_u32_e32 v10, s29, v208
	s_min_u32 s26, s26, s12
	s_lshl_b32 s92, s28, 13
	s_waitcnt vmcnt(3)
	ds_write_b128 v208, v[152:155]
	s_waitcnt vmcnt(2)
	ds_write_b128 v10, v[156:159] offset:36864
	s_add_u32 vcc_lo, s100, s92
	s_addc_u32 vcc_hi, s101, 0
	global_load_dwordx4 v[10:13], v248, vcc
	s_lshl_b32 s92, s26, 7
	s_add_u32 vcc_lo, s98, s92
	s_addc_u32 vcc_hi, s99, 0
	global_load_dwordx4 v[160:163], v249, vcc
	s_add_i32 s29, s27, 1
	s_setprio 1
	v_cvt_pk_bf16_f32 v96, v166, v167
	v_cvt_pk_bf16_f32 v97, v210, v211
	v_cvt_pk_bf16_f32 v98, v212, v213
	v_cvt_pk_bf16_f32 v99, v214, v215
	s_waitcnt lgkmcnt(8)
	s_nop 0
	v_mfma_f32_32x32x16_bf16 v[16:31], v[68:71], v[96:99], v[16:31]
	v_add_f32_e32 v184, v166, v167
	v_add_f32_e32 v184, v184, v210
	v_add_f32_e32 v184, v184, v211
	s_nop 0
	v_mfma_f32_32x32x16_bf16 v[32:47], v[64:67], v[96:99], v[32:47]
	v_cvt_pk_bf16_f32 v68, v100, v101
	v_cvt_pk_bf16_f32 v69, v102, v103
	v_cvt_pk_bf16_f32 v70, v104, v105
	v_cvt_pk_bf16_f32 v71, v106, v107
	v_add_f32_e32 v184, v184, v212
	v_add_f32_e32 v184, v184, v213
	v_add_f32_e32 v184, v184, v214
	v_add_f32_e32 v184, v184, v215
	s_waitcnt lgkmcnt(7)
	v_mfma_f32_32x32x16_bf16 v[16:31], v[72:75], v[68:71], v[16:31]
	v_add_f32_e32 v184, v184, v100
	v_add_f32_e32 v184, v184, v101
	v_add_f32_e32 v184, v184, v102
	v_add_f32_e32 v184, v184, v103
	s_waitcnt lgkmcnt(6)
	v_mfma_f32_32x32x16_bf16 v[32:47], v[76:79], v[68:71], v[32:47]
	v_cvt_pk_bf16_f32 v64, v108, v109
	v_cvt_pk_bf16_f32 v65, v110, v111
	v_cvt_pk_bf16_f32 v66, v144, v145
	v_cvt_pk_bf16_f32 v67, v146, v147
	v_add_f32_e32 v184, v184, v104
	v_add_f32_e32 v184, v184, v105
	v_add_f32_e32 v184, v184, v106
	v_add_f32_e32 v184, v184, v107
	s_waitcnt lgkmcnt(5)
	v_mfma_f32_32x32x16_bf16 v[16:31], v[80:83], v[64:67], v[16:31]
	v_add_f32_e32 v184, v184, v108
	v_add_f32_e32 v184, v184, v109
	v_add_f32_e32 v184, v184, v110
	v_add_f32_e32 v184, v184, v111
	s_waitcnt lgkmcnt(4)
	v_mfma_f32_32x32x16_bf16 v[32:47], v[84:87], v[64:67], v[32:47]
	v_cvt_pk_bf16_f32 v68, v216, v217
	v_cvt_pk_bf16_f32 v69, v218, v219
	v_cvt_pk_bf16_f32 v70, v148, v149
	v_cvt_pk_bf16_f32 v71, v150, v151
	v_add_f32_e32 v184, v184, v144
	v_add_f32_e32 v184, v184, v145
	v_add_f32_e32 v184, v184, v146
	v_add_f32_e32 v184, v184, v147
	s_waitcnt lgkmcnt(3)
	v_mfma_f32_32x32x16_bf16 v[16:31], v[88:91], v[68:71], v[16:31]
	v_add_f32_e32 v184, v184, v216
	v_add_f32_e32 v184, v184, v217
	v_add_f32_e32 v184, v184, v218
	v_add_f32_e32 v184, v184, v219
	s_waitcnt lgkmcnt(2)
	v_mfma_f32_32x32x16_bf16 v[32:47], v[92:95], v[68:71], v[32:47]
	v_add_f32_e32 v184, v184, v148
	v_add_f32_e32 v184, v184, v149
	v_add_f32_e32 v184, v184, v150
	v_add_f32_e32 v184, v184, v151
	s_setprio 0
	ds_read_b128 v[68:71], v195 offset:27680
	ds_read_b128 v[76:79], v195 offset:32288
	ds_read_b128 v[80:83], v195 offset:27712
	ds_read_b128 v[84:87], v195 offset:27744
	ds_read_b128 v[88:91], v195 offset:32320
	ds_read_b128 v[92:95], v195 offset:32352
	s_cmp_lg_u32 s27, 4
	s_cselect_b32 s26, s29, 0
	s_waitcnt lgkmcnt(6)
	v_mfma_f32_32x32x16_bf16 v[144:159], v[240:243], v[180:183], v[48:63]
	v_exp_f32_e32 v166, v128
	v_exp_f32_e32 v167, v129
	v_exp_f32_e32 v185, v130
	v_exp_f32_e32 v186, v131
	s_waitcnt lgkmcnt(5)
	v_mfma_f32_32x32x16_bf16 v[96:111], v[244:247], v[180:183], v[48:63]
	v_exp_f32_e32 v128, v132
	v_exp_f32_e32 v129, v133
	v_exp_f32_e32 v130, v134
	v_exp_f32_e32 v131, v135
	v_mfma_f32_32x32x16_bf16 v[144:159], v[68:71], v[176:179], v[144:159]
	v_exp_f32_e32 v132, v136
	v_exp_f32_e32 v133, v137
	v_exp_f32_e32 v134, v138
	v_exp_f32_e32 v135, v139
	s_waitcnt lgkmcnt(4)
	v_mfma_f32_32x32x16_bf16 v[96:111], v[76:79], v[176:179], v[96:111]
	v_exp_f32_e32 v136, v140
	v_exp_f32_e32 v137, v141
	v_exp_f32_e32 v138, v142
	v_exp_f32_e32 v139, v143
	s_waitcnt lgkmcnt(3)
	v_mfma_f32_32x32x16_bf16 v[144:159], v[80:83], v[172:175], v[144:159]
	v_exp_f32_e32 v140, v112
	v_exp_f32_e32 v141, v113
	v_exp_f32_e32 v142, v114
	v_exp_f32_e32 v143, v115
	s_waitcnt lgkmcnt(1)
	v_mfma_f32_32x32x16_bf16 v[96:111], v[88:91], v[172:175], v[96:111]
	v_exp_f32_e32 v187, v116
	v_exp_f32_e32 v210, v117
	v_exp_f32_e32 v211, v118
	v_exp_f32_e32 v212, v119
	v_mfma_f32_32x32x16_bf16 v[144:159], v[84:87], v[168:171], v[144:159]
	v_exp_f32_e32 v116, v120
	v_exp_f32_e32 v117, v121
	v_exp_f32_e32 v118, v122
	v_exp_f32_e32 v119, v123
	s_waitcnt lgkmcnt(0)
	v_mfma_f32_32x32x16_bf16 v[96:111], v[92:95], v[168:171], v[96:111]
	v_exp_f32_e32 v120, v124
	v_exp_f32_e32 v121, v125
	v_exp_f32_e32 v122, v126
	v_exp_f32_e32 v123, v127
	s_cmp_gt_i32 s26, 2
	s_cselect_b32 s27, -3, 2
	s_add_i32 s27, s27, s26
	s_mulk_i32 s27, 0x2400
	s_waitcnt vmcnt(3)
	ds_write_b128 v208, v[2:5] offset:9216
	v_add_u32_e32 v2, s27, v208
	s_add_i32 s27, s26, 1
	s_cmp_lg_u32 s26, 4
	s_cselect_b32 s26, s27, 0
	s_add_i32 s27, s13, -5
	s_min_u32 s27, s27, s12
	s_lshl_b32 s92, s27, 13
	s_waitcnt vmcnt(2)
	ds_write_b128 v2, v[6:9] offset:36864
	s_add_u32 vcc_lo, s100, s92
	s_addc_u32 vcc_hi, s101, 0
	global_load_dwordx4 v[6:9], v248, vcc
	s_lshl_b32 s92, s28, 7
	s_add_u32 vcc_lo, s98, s92
	s_addc_u32 vcc_hi, s99, 0
	global_load_dwordx4 v[2:5], v249, vcc
	s_nop 0
	s_mul_i32 s28, s26, 0x2400
	s_add_i32 s29, s28, 0xffffdc00
	s_cmp_lg_u32 s26, 0
	s_cselect_b32 s29, s29, 0x9000
	v_add_u32_e32 v92, s29, v195
	ds_read_b128 v[64:67], v92 offset:36864
	ds_read_b128 v[68:71], v92 offset:36896
	ds_read_b128 v[72:75], v92 offset:41472
	ds_read_b128 v[76:79], v92 offset:41504
	ds_read_b128 v[80:83], v92 offset:36928
	ds_read_b128 v[84:87], v92 offset:36960
	ds_read_b128 v[88:91], v92 offset:41536
	ds_read_b128 v[92:95], v92 offset:41568
	s_setprio 3
	v_cvt_pk_bf16_f32 v112, v166, v167
	v_cvt_pk_bf16_f32 v113, v185, v186
	v_cvt_pk_bf16_f32 v114, v128, v129
	v_cvt_pk_bf16_f32 v115, v130, v131
	s_waitcnt lgkmcnt(7)
	s_nop 0
	v_mfma_f32_32x32x16_bf16 v[16:31], v[64:67], v[112:115], v[16:31]
	v_add_f32_e32 v213, v166, v167
	v_add_f32_e32 v213, v213, v185
	v_add_f32_e32 v213, v213, v186
	s_waitcnt lgkmcnt(5)
	v_mfma_f32_32x32x16_bf16 v[32:47], v[72:75], v[112:115], v[32:47]
	v_cvt_pk_bf16_f32 v64, v132, v133
	v_cvt_pk_bf16_f32 v65, v134, v135
	v_cvt_pk_bf16_f32 v66, v136, v137
	v_cvt_pk_bf16_f32 v67, v138, v139
	v_add_f32_e32 v213, v213, v128
	v_add_f32_e32 v213, v213, v129
	v_add_f32_e32 v213, v213, v130
	v_add_f32_e32 v213, v213, v131
	s_nop 0
	v_mfma_f32_32x32x16_bf16 v[16:31], v[68:71], v[64:67], v[16:31]
	v_add_f32_e32 v213, v213, v132
	v_add_f32_e32 v213, v213, v133
	v_add_f32_e32 v213, v213, v134
	v_add_f32_e32 v213, v213, v135
	s_waitcnt lgkmcnt(4)
	v_mfma_f32_32x32x16_bf16 v[32:47], v[76:79], v[64:67], v[32:47]
	v_cvt_pk_bf16_f32 v68, v140, v141
	v_cvt_pk_bf16_f32 v69, v142, v143
	v_cvt_pk_bf16_f32 v70, v187, v210
	v_cvt_pk_bf16_f32 v71, v211, v212
	v_add_f32_e32 v213, v213, v136
	v_add_f32_e32 v213, v213, v137
	v_add_f32_e32 v213, v213, v138
	v_add_f32_e32 v213, v213, v139
	s_waitcnt lgkmcnt(3)
	v_mfma_f32_32x32x16_bf16 v[16:31], v[80:83], v[68:71], v[16:31]
	v_add_f32_e32 v213, v213, v140
	v_add_f32_e32 v213, v213, v141
	v_add_f32_e32 v213, v213, v142
	v_add_f32_e32 v213, v213, v143
	s_waitcnt lgkmcnt(1)
	v_mfma_f32_32x32x16_bf16 v[32:47], v[88:91], v[68:71], v[32:47]
	v_cvt_pk_bf16_f32 v64, v116, v117
	v_cvt_pk_bf16_f32 v65, v118, v119
	v_cvt_pk_bf16_f32 v66, v120, v121
	v_cvt_pk_bf16_f32 v67, v122, v123
	v_add_f32_e32 v213, v213, v187
	v_add_f32_e32 v213, v213, v210
	v_add_f32_e32 v213, v213, v211
	v_add_f32_e32 v213, v213, v212
	s_nop 0
	v_mfma_f32_32x32x16_bf16 v[16:31], v[84:87], v[64:67], v[16:31]
	v_add_f32_e32 v213, v213, v116
	v_add_f32_e32 v213, v213, v117
	v_add_f32_e32 v213, v213, v118
	v_add_f32_e32 v213, v213, v119
	s_waitcnt lgkmcnt(0)
	v_mfma_f32_32x32x16_bf16 v[32:47], v[92:95], v[64:67], v[32:47]
	v_add_f32_e32 v213, v213, v120
	v_add_f32_e32 v213, v213, v121
	v_add_f32_e32 v213, v213, v122
	v_add_f32_e32 v213, v213, v123
	s_setprio 2
	s_waitcnt lgkmcnt(0)
	s_barrier
	ds_read_b128 v[240:243], v195
	ds_read_b128 v[244:247], v195 offset:4608
	ds_read_b128 v[116:119], v195 offset:32
	ds_read_b128 v[120:123], v195 offset:4640
	ds_read_b128 v[124:127], v195 offset:64
	ds_read_b128 v[128:131], v195 offset:4672
	ds_read_b128 v[132:135], v195 offset:96
	ds_read_b128 v[136:139], v195 offset:4704
	v_add_f32_e32 v1, v1, v184
	v_exp_f32_e32 v140, v144
	v_exp_f32_e32 v141, v145
	v_exp_f32_e32 v142, v146
	v_exp_f32_e32 v143, v147
	s_waitcnt lgkmcnt(6)
	v_mfma_f32_32x32x16_bf16 v[80:95], v[240:243], v[180:183], v[48:63]
	v_mfma_f32_32x32x16_bf16 v[64:79], v[244:247], v[180:183], v[48:63]
	v_exp_f32_e32 v144, v148
	v_exp_f32_e32 v145, v149
	v_exp_f32_e32 v146, v150
	v_exp_f32_e32 v147, v151
	s_waitcnt lgkmcnt(5)
	v_mfma_f32_32x32x16_bf16 v[80:95], v[116:119], v[176:179], v[80:95]
	v_exp_f32_e32 v148, v152
	v_exp_f32_e32 v149, v153
	v_exp_f32_e32 v150, v154
	v_exp_f32_e32 v151, v155
	s_waitcnt lgkmcnt(4)
	v_mfma_f32_32x32x16_bf16 v[64:79], v[120:123], v[176:179], v[64:79]
	v_exp_f32_e32 v152, v156
	v_exp_f32_e32 v153, v157
	v_exp_f32_e32 v154, v158
	v_exp_f32_e32 v155, v159
	s_waitcnt lgkmcnt(3)
	v_mfma_f32_32x32x16_bf16 v[80:95], v[124:127], v[172:175], v[80:95]
	v_exp_f32_e32 v156, v96
	v_exp_f32_e32 v157, v97
	v_exp_f32_e32 v158, v98
	v_exp_f32_e32 v159, v99
	s_waitcnt lgkmcnt(2)
	v_mfma_f32_32x32x16_bf16 v[64:79], v[128:131], v[172:175], v[64:79]
	v_exp_f32_e32 v166, v100
	v_exp_f32_e32 v167, v101
	v_exp_f32_e32 v184, v102
	v_exp_f32_e32 v185, v103
	s_waitcnt lgkmcnt(1)
	v_mfma_f32_32x32x16_bf16 v[80:95], v[132:135], v[168:171], v[80:95]
	v_exp_f32_e32 v186, v104
	v_exp_f32_e32 v187, v105
	v_exp_f32_e32 v210, v106
	v_exp_f32_e32 v211, v107
	s_waitcnt lgkmcnt(0)
	v_mfma_f32_32x32x16_bf16 v[64:79], v[136:139], v[168:171], v[64:79]
	v_exp_f32_e32 v212, v108
	v_exp_f32_e32 v214, v109
	v_exp_f32_e32 v215, v110
	v_exp_f32_e32 v216, v111
	v_add_u32_e32 v124, s28, v195
	ds_read_b128 v[240:243], v195 offset:9216
	ds_read_b128 v[244:247], v195 offset:13824
	ds_read_b128 v[96:99], v124 offset:41472
	ds_read_b128 v[100:103], v124 offset:36864
	ds_read_b128 v[104:107], v124 offset:36896
	ds_read_b128 v[108:111], v124 offset:41504
	ds_read_b128 v[112:115], v124 offset:36928
	ds_read_b128 v[116:119], v124 offset:41536
	ds_read_b128 v[120:123], v124 offset:36960
	ds_read_b128 v[124:127], v124 offset:41568
	s_cmp_gt_i32 s26, 2
	s_cselect_b32 s29, -3, 2
	s_add_i32 s29, s29, s26
	s_mulk_i32 s29, 0x2400
	s_waitcnt vmcnt(3)
	ds_write_b128 v208, v[10:13] offset:18432
	v_add_u32_e32 v10, s29, v208
	s_mov_b32 s29, 0x1da90000
	s_waitcnt vmcnt(2)
	ds_write_b128 v10, v[160:163] offset:36864
	s_add_i32 s92, s13, -4
	s_lshl_b32 s92, s92, 13
	s_add_u32 vcc_lo, s100, s92
	s_addc_u32 vcc_hi, s101, 0
	global_load_dwordx4 v[128:131], v248, vcc
	s_lshl_b32 s92, s27, 7
	s_add_u32 vcc_lo, s98, s92
	s_addc_u32 vcc_hi, s99, 0
	global_load_dwordx4 v[10:13], v249, vcc
	v_add_f32_e32 v1, v1, v213
	s_add_i32 s28, s26, 1
	s_setprio 1
	v_cvt_pk_bf16_f32 v132, v140, v141
	v_cvt_pk_bf16_f32 v133, v142, v143
	v_cvt_pk_bf16_f32 v134, v144, v145
	v_cvt_pk_bf16_f32 v135, v146, v147
	s_waitcnt lgkmcnt(8)
	s_nop 0
	v_mfma_f32_32x32x16_bf16 v[16:31], v[100:103], v[132:135], v[16:31]
	v_add_f32_e32 v160, v140, v141
	v_add_f32_e32 v160, v160, v142
	v_add_f32_e32 v160, v160, v143
	s_nop 0
	v_mfma_f32_32x32x16_bf16 v[32:47], v[96:99], v[132:135], v[32:47]
	v_cvt_pk_bf16_f32 v100, v148, v149
	v_cvt_pk_bf16_f32 v101, v150, v151
	v_cvt_pk_bf16_f32 v102, v152, v153
	v_cvt_pk_bf16_f32 v103, v154, v155
	v_add_f32_e32 v160, v160, v144
	v_add_f32_e32 v160, v160, v145
	v_add_f32_e32 v160, v160, v146
	v_add_f32_e32 v160, v160, v147
	s_waitcnt lgkmcnt(7)
	v_mfma_f32_32x32x16_bf16 v[16:31], v[104:107], v[100:103], v[16:31]
	v_add_f32_e32 v160, v160, v148
	v_add_f32_e32 v160, v160, v149
	v_add_f32_e32 v160, v160, v150
	v_add_f32_e32 v160, v160, v151
	s_waitcnt lgkmcnt(6)
	v_mfma_f32_32x32x16_bf16 v[32:47], v[108:111], v[100:103], v[32:47]
	v_cvt_pk_bf16_f32 v96, v156, v157
	v_cvt_pk_bf16_f32 v97, v158, v159
	v_cvt_pk_bf16_f32 v98, v166, v167
	v_cvt_pk_bf16_f32 v99, v184, v185
	v_add_f32_e32 v160, v160, v152
	v_add_f32_e32 v160, v160, v153
	v_add_f32_e32 v160, v160, v154
	v_add_f32_e32 v160, v160, v155
	s_waitcnt lgkmcnt(5)
	v_mfma_f32_32x32x16_bf16 v[16:31], v[112:115], v[96:99], v[16:31]
	v_add_f32_e32 v160, v160, v156
	v_add_f32_e32 v160, v160, v157
	v_add_f32_e32 v160, v160, v158
	v_add_f32_e32 v160, v160, v159
	s_waitcnt lgkmcnt(4)
	v_mfma_f32_32x32x16_bf16 v[32:47], v[116:119], v[96:99], v[32:47]
	v_cvt_pk_bf16_f32 v100, v186, v187
	v_cvt_pk_bf16_f32 v101, v210, v211
	v_cvt_pk_bf16_f32 v102, v212, v214
	v_cvt_pk_bf16_f32 v103, v215, v216
	v_add_f32_e32 v160, v160, v166
	v_add_f32_e32 v160, v160, v167
	v_add_f32_e32 v160, v160, v184
	v_add_f32_e32 v160, v160, v185
	s_waitcnt lgkmcnt(3)
	v_mfma_f32_32x32x16_bf16 v[16:31], v[120:123], v[100:103], v[16:31]
	v_add_f32_e32 v160, v160, v186
	v_add_f32_e32 v160, v160, v187
	v_add_f32_e32 v160, v160, v210
	v_add_f32_e32 v160, v160, v211
	s_waitcnt lgkmcnt(2)
	v_mfma_f32_32x32x16_bf16 v[32:47], v[124:127], v[100:103], v[32:47]
	v_add_f32_e32 v160, v160, v212
	v_add_f32_e32 v160, v160, v214
	v_add_f32_e32 v160, v160, v215
	v_add_f32_e32 v160, v160, v216
	s_setprio 0
	ds_read_b128 v[132:135], v195 offset:9248
	ds_read_b128 v[140:143], v195 offset:13856
	ds_read_b128 v[144:147], v195 offset:9280
	ds_read_b128 v[148:151], v195 offset:9312
	ds_read_b128 v[152:155], v195 offset:13888
	ds_read_b128 v[156:159], v195 offset:13920
	s_cmp_lg_u32 s26, 4
	s_cselect_b32 s26, s28, 0
	s_waitcnt lgkmcnt(6)
	v_mfma_f32_32x32x16_bf16 v[112:127], v[240:243], v[180:183], v[48:63]
	v_exp_f32_e32 v161, v80
	v_exp_f32_e32 v162, v81
	v_exp_f32_e32 v163, v82
	v_exp_f32_e32 v164, v83
	s_waitcnt lgkmcnt(5)
	v_mfma_f32_32x32x16_bf16 v[96:111], v[244:247], v[180:183], v[48:63]
	v_exp_f32_e32 v165, v84
	v_exp_f32_e32 v166, v85
	v_exp_f32_e32 v167, v86
	v_exp_f32_e32 v184, v87
	v_mfma_f32_32x32x16_bf16 v[112:127], v[132:135], v[176:179], v[112:127]
	v_exp_f32_e32 v136, v88
	v_exp_f32_e32 v137, v89
	v_exp_f32_e32 v138, v90
	v_exp_f32_e32 v139, v91
	s_waitcnt lgkmcnt(4)
	v_mfma_f32_32x32x16_bf16 v[96:111], v[140:143], v[176:179], v[96:111]
	v_exp_f32_e32 v185, v92
	v_exp_f32_e32 v186, v93
	v_exp_f32_e32 v187, v94
	v_exp_f32_e32 v210, v95
	s_waitcnt lgkmcnt(3)
	v_mfma_f32_32x32x16_bf16 v[112:127], v[144:147], v[172:175], v[112:127]
	v_exp_f32_e32 v140, v64
	v_exp_f32_e32 v141, v65
	v_exp_f32_e32 v142, v66
	v_exp_f32_e32 v143, v67
	s_waitcnt lgkmcnt(1)
	v_mfma_f32_32x32x16_bf16 v[96:111], v[152:155], v[172:175], v[96:111]
	v_exp_f32_e32 v144, v68
	v_exp_f32_e32 v145, v69
	v_exp_f32_e32 v146, v70
	v_exp_f32_e32 v147, v71
	v_mfma_f32_32x32x16_bf16 v[112:127], v[148:151], v[168:171], v[112:127]
	v_exp_f32_e32 v152, v72
	v_exp_f32_e32 v153, v73
	v_exp_f32_e32 v154, v74
	v_exp_f32_e32 v155, v75
	s_waitcnt lgkmcnt(0)
	v_mfma_f32_32x32x16_bf16 v[96:111], v[156:159], v[168:171], v[96:111]
	v_exp_f32_e32 v148, v76
	v_exp_f32_e32 v149, v77
	v_exp_f32_e32 v150, v78
	v_exp_f32_e32 v151, v79
	s_cmp_gt_i32 s26, 2
	s_cselect_b32 s27, -3, 2
	s_add_i32 s27, s27, s26
	s_mulk_i32 s27, 0x2400
	s_waitcnt vmcnt(3)
	ds_write_b128 v208, v[6:9] offset:27648
	v_add_u32_e32 v6, s27, v208
	s_add_i32 s27, s26, 1
	s_cmp_lg_u32 s26, 4
	s_cselect_b32 s27, s27, 0
	s_add_i32 s26, s13, -3
	s_min_u32 s28, s26, s12
	s_lshl_b32 s92, s28, 13
	s_waitcnt vmcnt(2)
	ds_write_b128 v6, v[2:5] offset:36864
	s_add_u32 vcc_lo, s100, s92
	s_addc_u32 vcc_hi, s101, 0
	global_load_dwordx4 v[6:9], v248, vcc
	s_nop 0
	s_add_i32 s92, s13, -4
	s_lshl_b32 s92, s92, 7
	s_add_u32 vcc_lo, s98, s92
	s_addc_u32 vcc_hi, s99, 0
	global_load_dwordx4 v[2:5], v249, vcc
	s_mul_i32 s29, s27, 0x2400
	s_add_i32 s34, s29, 0xffffdc00
	s_cmp_lg_u32 s27, 0
	s_cselect_b32 s34, s34, 0x9000
	v_add_u32_e32 v14, s34, v195
	ds_read_b128 v[64:67], v14 offset:36864
	ds_read_b128 v[68:71], v14 offset:36896
	ds_read_b128 v[72:75], v14 offset:41472
	ds_read_b128 v[76:79], v14 offset:41504
	ds_read_b128 v[80:83], v14 offset:36928
	ds_read_b128 v[84:87], v14 offset:36960
	ds_read_b128 v[88:91], v14 offset:41536
	ds_read_b128 v[92:95], v14 offset:41568
	s_setprio 3
	v_cvt_pk_bf16_f32 v132, v161, v162
	v_cvt_pk_bf16_f32 v133, v163, v164
	v_cvt_pk_bf16_f32 v134, v165, v166
	v_cvt_pk_bf16_f32 v135, v167, v184
	s_waitcnt lgkmcnt(7)
	s_nop 0
	v_mfma_f32_32x32x16_bf16 v[16:31], v[64:67], v[132:135], v[16:31]
	v_add_f32_e32 v14, v161, v162
	v_add_f32_e32 v14, v14, v163
	v_add_f32_e32 v14, v14, v164
	s_waitcnt lgkmcnt(5)
	v_mfma_f32_32x32x16_bf16 v[32:47], v[72:75], v[132:135], v[32:47]
	v_cvt_pk_bf16_f32 v64, v136, v137
	v_cvt_pk_bf16_f32 v65, v138, v139
	v_cvt_pk_bf16_f32 v66, v185, v186
	v_cvt_pk_bf16_f32 v67, v187, v210
	v_add_f32_e32 v14, v14, v165
	v_add_f32_e32 v14, v14, v166
	v_add_f32_e32 v14, v14, v167
	v_add_f32_e32 v14, v14, v184
	s_nop 0
	v_mfma_f32_32x32x16_bf16 v[16:31], v[68:71], v[64:67], v[16:31]
	v_add_f32_e32 v14, v14, v136
	v_add_f32_e32 v14, v14, v137
	v_add_f32_e32 v14, v14, v138
	v_add_f32_e32 v14, v14, v139
	s_waitcnt lgkmcnt(4)
	v_mfma_f32_32x32x16_bf16 v[32:47], v[76:79], v[64:67], v[32:47]
	v_cvt_pk_bf16_f32 v68, v140, v141
	v_cvt_pk_bf16_f32 v69, v142, v143
	v_cvt_pk_bf16_f32 v70, v144, v145
	v_cvt_pk_bf16_f32 v71, v146, v147
	v_add_f32_e32 v14, v14, v185
	v_add_f32_e32 v14, v14, v186
	v_add_f32_e32 v14, v14, v187
	v_add_f32_e32 v14, v14, v210
	s_waitcnt lgkmcnt(3)
	v_mfma_f32_32x32x16_bf16 v[16:31], v[80:83], v[68:71], v[16:31]
	v_add_f32_e32 v14, v14, v140
	v_add_f32_e32 v14, v14, v141
	v_add_f32_e32 v14, v14, v142
	v_add_f32_e32 v14, v14, v143
	s_waitcnt lgkmcnt(1)
	v_mfma_f32_32x32x16_bf16 v[32:47], v[88:91], v[68:71], v[32:47]
	v_cvt_pk_bf16_f32 v64, v152, v153
	v_cvt_pk_bf16_f32 v65, v154, v155
	v_cvt_pk_bf16_f32 v66, v148, v149
	v_cvt_pk_bf16_f32 v67, v150, v151
	v_add_f32_e32 v14, v14, v144
	v_add_f32_e32 v14, v14, v145
	v_add_f32_e32 v14, v14, v146
	v_add_f32_e32 v14, v14, v147
	s_nop 0
	v_mfma_f32_32x32x16_bf16 v[16:31], v[84:87], v[64:67], v[16:31]
	v_add_f32_e32 v14, v14, v152
	v_add_f32_e32 v14, v14, v153
	v_add_f32_e32 v14, v14, v154
	v_add_f32_e32 v14, v14, v155
	s_waitcnt lgkmcnt(0)
	v_mfma_f32_32x32x16_bf16 v[32:47], v[92:95], v[64:67], v[32:47]
	v_add_f32_e32 v14, v14, v148
	v_add_f32_e32 v14, v14, v149
	v_add_f32_e32 v14, v14, v150
	v_add_f32_e32 v14, v14, v151
	s_setprio 2
	s_waitcnt lgkmcnt(0)
	s_barrier
	ds_read_b128 v[240:243], v195 offset:18432
	ds_read_b128 v[244:247], v195 offset:23040
	ds_read_b128 v[136:139], v195 offset:18464
	ds_read_b128 v[140:143], v195 offset:23072
	ds_read_b128 v[144:147], v195 offset:18496
	ds_read_b128 v[148:151], v195 offset:23104
	ds_read_b128 v[152:155], v195 offset:18528
	ds_read_b128 v[156:159], v195 offset:23136
	v_add_f32_e32 v1, v1, v160
	v_exp_f32_e32 v160, v112
	v_exp_f32_e32 v161, v113
	v_exp_f32_e32 v162, v114
	v_exp_f32_e32 v163, v115
	s_waitcnt lgkmcnt(6)
	v_mfma_f32_32x32x16_bf16 v[80:95], v[240:243], v[180:183], v[48:63]
	v_mfma_f32_32x32x16_bf16 v[64:79], v[244:247], v[180:183], v[48:63]
	v_exp_f32_e32 v164, v116
	v_exp_f32_e32 v165, v117
	v_exp_f32_e32 v166, v118
	v_exp_f32_e32 v167, v119
	s_waitcnt lgkmcnt(5)
	v_mfma_f32_32x32x16_bf16 v[80:95], v[136:139], v[176:179], v[80:95]
	v_exp_f32_e32 v184, v120
	v_exp_f32_e32 v185, v121
	v_exp_f32_e32 v186, v122
	v_exp_f32_e32 v187, v123
	s_waitcnt lgkmcnt(4)
	v_mfma_f32_32x32x16_bf16 v[64:79], v[140:143], v[176:179], v[64:79]
	v_exp_f32_e32 v136, v124
	v_exp_f32_e32 v137, v125
	v_exp_f32_e32 v138, v126
	v_exp_f32_e32 v139, v127
	s_waitcnt lgkmcnt(3)
	v_mfma_f32_32x32x16_bf16 v[80:95], v[144:147], v[172:175], v[80:95]
	v_exp_f32_e32 v140, v96
	v_exp_f32_e32 v141, v97
	v_exp_f32_e32 v142, v98
	v_exp_f32_e32 v143, v99
	s_waitcnt lgkmcnt(2)
	v_mfma_f32_32x32x16_bf16 v[64:79], v[148:151], v[172:175], v[64:79]
	v_exp_f32_e32 v144, v100
	v_exp_f32_e32 v145, v101
	v_exp_f32_e32 v146, v102
	v_exp_f32_e32 v147, v103
	s_waitcnt lgkmcnt(1)
	v_mfma_f32_32x32x16_bf16 v[80:95], v[152:155], v[168:171], v[80:95]
	v_exp_f32_e32 v148, v104
	v_exp_f32_e32 v149, v105
	v_exp_f32_e32 v150, v106
	v_exp_f32_e32 v151, v107
	s_waitcnt lgkmcnt(0)
	v_mfma_f32_32x32x16_bf16 v[64:79], v[156:159], v[168:171], v[64:79]
	v_exp_f32_e32 v152, v108
	v_exp_f32_e32 v153, v109
	v_exp_f32_e32 v154, v110
	v_exp_f32_e32 v155, v111
	s_cmp_gt_i32 s27, 2
	s_cselect_b32 s34, -3, 2
	s_waitcnt vmcnt(3)
	ds_write_b128 v208, v[128:131]
	v_add_u32_e32 v128, s29, v195
	ds_read_b128 v[240:243], v195 offset:27648
	ds_read_b128 v[244:247], v195 offset:32256
	ds_read_b128 v[96:99], v128 offset:41472
	ds_read_b128 v[100:103], v128 offset:36864
	ds_read_b128 v[104:107], v128 offset:36896
	ds_read_b128 v[108:111], v128 offset:41504
	ds_read_b128 v[116:119], v128 offset:36928
	ds_read_b128 v[120:123], v128 offset:41536
	ds_read_b128 v[124:127], v128 offset:36960
	ds_read_b128 v[128:131], v128 offset:41568
	s_add_i32 s34, s34, s27
	s_add_i32 s29, s13, -2
	s_mulk_i32 s34, 0x2400
	s_min_u32 s29, s29, s12
	v_add_u32_e32 v15, s34, v208
	s_lshl_b32 s92, s29, 13
	s_waitcnt vmcnt(2)
	ds_write_b128 v15, v[10:13] offset:36864
	s_add_u32 vcc_lo, s100, s92
	s_addc_u32 vcc_hi, s101, 0
	global_load_dwordx4 v[10:13], v248, vcc
	s_lshl_b32 s92, s28, 7
	v_add_f32_e32 v1, v1, v14
	s_add_u32 vcc_lo, s98, s92
	s_addc_u32 vcc_hi, s99, 0
	global_load_dwordx4 v[112:115], v249, vcc
	s_add_i32 s34, s27, 1
	s_setprio 1
	v_cvt_pk_bf16_f32 v132, v160, v161
	v_cvt_pk_bf16_f32 v133, v162, v163
	v_cvt_pk_bf16_f32 v134, v164, v165
	v_cvt_pk_bf16_f32 v135, v166, v167
	s_waitcnt lgkmcnt(7)
	s_nop 0
	v_mfma_f32_32x32x16_bf16 v[16:31], v[100:103], v[132:135], v[16:31]
	v_add_f32_e32 v14, v160, v161
	v_add_f32_e32 v14, v14, v162
	v_add_f32_e32 v14, v14, v163
	s_nop 0
	v_mfma_f32_32x32x16_bf16 v[32:47], v[96:99], v[132:135], v[32:47]
	v_cvt_pk_bf16_f32 v100, v184, v185
	v_cvt_pk_bf16_f32 v101, v186, v187
	v_cvt_pk_bf16_f32 v102, v136, v137
	v_cvt_pk_bf16_f32 v103, v138, v139
	v_add_f32_e32 v14, v14, v164
	v_add_f32_e32 v14, v14, v165
	v_add_f32_e32 v14, v14, v166
	v_add_f32_e32 v14, v14, v167
	s_waitcnt lgkmcnt(6)
	v_mfma_f32_32x32x16_bf16 v[16:31], v[104:107], v[100:103], v[16:31]
	v_add_f32_e32 v14, v14, v184
	v_add_f32_e32 v14, v14, v185
	v_add_f32_e32 v14, v14, v186
	v_add_f32_e32 v14, v14, v187
	s_waitcnt lgkmcnt(5)
	v_mfma_f32_32x32x16_bf16 v[32:47], v[108:111], v[100:103], v[32:47]
	v_cvt_pk_bf16_f32 v96, v140, v141
	v_cvt_pk_bf16_f32 v97, v142, v143
	v_cvt_pk_bf16_f32 v98, v144, v145
	v_cvt_pk_bf16_f32 v99, v146, v147
	v_add_f32_e32 v14, v14, v136
	v_add_f32_e32 v14, v14, v137
	v_add_f32_e32 v14, v14, v138
	v_add_f32_e32 v14, v14, v139
	s_waitcnt lgkmcnt(4)
	v_mfma_f32_32x32x16_bf16 v[16:31], v[116:119], v[96:99], v[16:31]
	v_add_f32_e32 v14, v14, v140
	v_add_f32_e32 v14, v14, v141
	v_add_f32_e32 v14, v14, v142
	v_add_f32_e32 v14, v14, v143
	s_waitcnt lgkmcnt(3)
	v_mfma_f32_32x32x16_bf16 v[32:47], v[120:123], v[96:99], v[32:47]
	v_cvt_pk_bf16_f32 v100, v148, v149
	v_cvt_pk_bf16_f32 v101, v150, v151
	v_cvt_pk_bf16_f32 v102, v152, v153
	v_cvt_pk_bf16_f32 v103, v154, v155
	v_add_f32_e32 v14, v14, v144
	v_add_f32_e32 v14, v14, v145
	v_add_f32_e32 v14, v14, v146
	v_add_f32_e32 v14, v14, v147
	s_waitcnt lgkmcnt(2)
	v_mfma_f32_32x32x16_bf16 v[16:31], v[124:127], v[100:103], v[16:31]
	v_add_f32_e32 v14, v14, v148
	v_add_f32_e32 v14, v14, v149
	v_add_f32_e32 v14, v14, v150
	v_add_f32_e32 v14, v14, v151
	s_waitcnt lgkmcnt(1)
	v_mfma_f32_32x32x16_bf16 v[32:47], v[128:131], v[100:103], v[32:47]
	v_add_f32_e32 v14, v14, v152
	v_add_f32_e32 v14, v14, v153
	v_add_f32_e32 v14, v14, v154
	v_add_f32_e32 v14, v14, v155
	s_setprio 0
	ds_read_b128 v[116:119], v195 offset:27680
	ds_read_b128 v[124:127], v195 offset:32288
	ds_read_b128 v[128:131], v195 offset:27712
	ds_read_b128 v[132:135], v195 offset:27744
	ds_read_b128 v[136:139], v195 offset:32320
	ds_read_b128 v[140:143], v195 offset:32352
	s_cmp_lg_u32 s27, 4
	s_cselect_b32 s27, s34, 0
	s_waitcnt lgkmcnt(6)
	v_mfma_f32_32x32x16_bf16 v[152:167], v[240:243], v[180:183], v[48:63]
	v_exp_f32_e32 v15, v80
	v_exp_f32_e32 v144, v81
	v_exp_f32_e32 v145, v82
	v_exp_f32_e32 v146, v83
	s_waitcnt lgkmcnt(5)
	v_mfma_f32_32x32x16_bf16 v[96:111], v[244:247], v[180:183], v[48:63]
	v_exp_f32_e32 v147, v84
	v_exp_f32_e32 v148, v85
	v_exp_f32_e32 v149, v86
	v_exp_f32_e32 v150, v87
	v_mfma_f32_32x32x16_bf16 v[152:167], v[116:119], v[176:179], v[152:167]
	v_exp_f32_e32 v120, v88
	v_exp_f32_e32 v121, v89
	v_exp_f32_e32 v122, v90
	v_exp_f32_e32 v123, v91
	s_waitcnt lgkmcnt(4)
	v_mfma_f32_32x32x16_bf16 v[96:111], v[124:127], v[176:179], v[96:111]
	v_exp_f32_e32 v151, v92
	v_exp_f32_e32 v184, v93
	v_exp_f32_e32 v185, v94
	v_exp_f32_e32 v186, v95
	s_waitcnt lgkmcnt(3)
	v_mfma_f32_32x32x16_bf16 v[152:167], v[128:131], v[172:175], v[152:167]
	v_exp_f32_e32 v124, v64
	v_exp_f32_e32 v125, v65
	v_exp_f32_e32 v126, v66
	v_exp_f32_e32 v127, v67
	s_waitcnt lgkmcnt(1)
	v_mfma_f32_32x32x16_bf16 v[96:111], v[136:139], v[172:175], v[96:111]
	v_exp_f32_e32 v128, v68
	v_exp_f32_e32 v129, v69
	v_exp_f32_e32 v130, v70
	v_exp_f32_e32 v131, v71
	v_mfma_f32_32x32x16_bf16 v[152:167], v[132:135], v[168:171], v[152:167]
	v_exp_f32_e32 v136, v72
	v_exp_f32_e32 v137, v73
	v_exp_f32_e32 v138, v74
	v_exp_f32_e32 v139, v75
	s_waitcnt lgkmcnt(0)
	v_mfma_f32_32x32x16_bf16 v[96:111], v[140:143], v[168:171], v[96:111]
	v_exp_f32_e32 v132, v76
	v_exp_f32_e32 v133, v77
	v_exp_f32_e32 v134, v78
	v_exp_f32_e32 v135, v79
	s_cmp_gt_i32 s27, 2
	s_cselect_b32 s28, -3, 2
	s_add_i32 s28, s28, s27
	s_mulk_i32 s28, 0x2400
	s_waitcnt vmcnt(3)
	ds_write_b128 v208, v[6:9] offset:9216
	v_add_u32_e32 v6, s28, v208
	s_add_i32 s28, s27, 1
	s_cmp_lg_u32 s27, 4
	s_cselect_b32 s27, s28, 0
	s_add_i32 s28, s13, -1
	s_min_u32 s28, s28, s12
	s_lshl_b32 s92, s28, 13
	s_waitcnt vmcnt(2)
	ds_write_b128 v6, v[2:5] offset:36864
	s_add_u32 vcc_lo, s100, s92
	s_addc_u32 vcc_hi, s101, 0
	global_load_dwordx4 v[6:9], v248, vcc
	s_lshl_b32 s92, s29, 7
	s_add_u32 vcc_lo, s98, s92
	s_addc_u32 vcc_hi, s99, 0
	global_load_dwordx4 v[2:5], v249, vcc
	s_nop 0
	s_mul_i32 s29, s27, 0x2400
	s_add_i32 s34, s29, 0xffffdc00
	s_cmp_lg_u32 s27, 0
	s_cselect_b32 s34, s34, 0x9000
	v_add_u32_e32 v92, s34, v195
	ds_read_b128 v[64:67], v92 offset:36864
	ds_read_b128 v[68:71], v92 offset:36896
	ds_read_b128 v[72:75], v92 offset:41472
	ds_read_b128 v[76:79], v92 offset:41504
	ds_read_b128 v[80:83], v92 offset:36928
	ds_read_b128 v[84:87], v92 offset:36960
	ds_read_b128 v[88:91], v92 offset:41536
	ds_read_b128 v[92:95], v92 offset:41568
	s_setprio 3
	v_cvt_pk_bf16_f32 v116, v15, v144
	v_cvt_pk_bf16_f32 v117, v145, v146
	v_cvt_pk_bf16_f32 v118, v147, v148
	v_cvt_pk_bf16_f32 v119, v149, v150
	s_waitcnt lgkmcnt(7)
	s_nop 0
	v_mfma_f32_32x32x16_bf16 v[16:31], v[64:67], v[116:119], v[16:31]
	v_add_f32_e32 v187, v15, v144
	v_add_f32_e32 v187, v187, v145
	v_add_f32_e32 v187, v187, v146
	s_waitcnt lgkmcnt(5)
	v_mfma_f32_32x32x16_bf16 v[32:47], v[72:75], v[116:119], v[32:47]
	v_cvt_pk_bf16_f32 v64, v120, v121
	v_cvt_pk_bf16_f32 v65, v122, v123
	v_cvt_pk_bf16_f32 v66, v151, v184
	v_cvt_pk_bf16_f32 v67, v185, v186
	v_add_f32_e32 v187, v187, v147
	v_add_f32_e32 v187, v187, v148
	v_add_f32_e32 v187, v187, v149
	v_add_f32_e32 v187, v187, v150
	s_nop 0
	v_mfma_f32_32x32x16_bf16 v[16:31], v[68:71], v[64:67], v[16:31]
	v_add_f32_e32 v187, v187, v120
	v_add_f32_e32 v187, v187, v121
	v_add_f32_e32 v187, v187, v122
	v_add_f32_e32 v187, v187, v123
	s_waitcnt lgkmcnt(4)
	v_mfma_f32_32x32x16_bf16 v[32:47], v[76:79], v[64:67], v[32:47]
	v_cvt_pk_bf16_f32 v68, v124, v125
	v_cvt_pk_bf16_f32 v69, v126, v127
	v_cvt_pk_bf16_f32 v70, v128, v129
	v_cvt_pk_bf16_f32 v71, v130, v131
	v_add_f32_e32 v187, v187, v151
	v_add_f32_e32 v187, v187, v184
	v_add_f32_e32 v187, v187, v185
	v_add_f32_e32 v187, v187, v186
	s_waitcnt lgkmcnt(3)
	v_mfma_f32_32x32x16_bf16 v[16:31], v[80:83], v[68:71], v[16:31]
	v_add_f32_e32 v187, v187, v124
	v_add_f32_e32 v187, v187, v125
	v_add_f32_e32 v187, v187, v126
	v_add_f32_e32 v187, v187, v127
	s_waitcnt lgkmcnt(1)
	v_mfma_f32_32x32x16_bf16 v[32:47], v[88:91], v[68:71], v[32:47]
	v_cvt_pk_bf16_f32 v64, v136, v137
	v_cvt_pk_bf16_f32 v65, v138, v139
	v_cvt_pk_bf16_f32 v66, v132, v133
	v_cvt_pk_bf16_f32 v67, v134, v135
	v_add_f32_e32 v187, v187, v128
	v_add_f32_e32 v187, v187, v129
	v_add_f32_e32 v187, v187, v130
	v_add_f32_e32 v187, v187, v131
	s_nop 0
	v_mfma_f32_32x32x16_bf16 v[16:31], v[84:87], v[64:67], v[16:31]
	v_add_f32_e32 v187, v187, v136
	v_add_f32_e32 v187, v187, v137
	v_add_f32_e32 v187, v187, v138
	v_add_f32_e32 v187, v187, v139
	s_waitcnt lgkmcnt(0)
	v_mfma_f32_32x32x16_bf16 v[32:47], v[92:95], v[64:67], v[32:47]
	v_add_f32_e32 v187, v187, v132
	v_add_f32_e32 v187, v187, v133
	v_add_f32_e32 v187, v187, v134
	v_add_f32_e32 v187, v187, v135
	s_setprio 2
	s_waitcnt lgkmcnt(0)
	s_barrier
	ds_read_b128 v[240:243], v195
	ds_read_b128 v[244:247], v195 offset:4608
	ds_read_b128 v[72:75], v195 offset:32
	ds_read_b128 v[76:79], v195 offset:4640
	ds_read_b128 v[80:83], v195 offset:64
	ds_read_b128 v[84:87], v195 offset:4672
	ds_read_b128 v[88:91], v195 offset:96
	ds_read_b128 v[92:95], v195 offset:4704
	v_add_f32_e32 v1, v1, v14
	v_exp_f32_e32 v14, v152
	v_exp_f32_e32 v15, v153
	v_exp_f32_e32 v116, v154
	v_exp_f32_e32 v117, v155
	s_waitcnt lgkmcnt(6)
	v_mfma_f32_32x32x16_bf16 v[136:151], v[240:243], v[180:183], v[48:63]
	v_mfma_f32_32x32x16_bf16 v[120:135], v[244:247], v[180:183], v[48:63]
	v_exp_f32_e32 v118, v156
	v_exp_f32_e32 v119, v157
	v_exp_f32_e32 v184, v158
	v_exp_f32_e32 v185, v159
	s_waitcnt lgkmcnt(5)
	v_mfma_f32_32x32x16_bf16 v[136:151], v[72:75], v[176:179], v[136:151]
	v_exp_f32_e32 v186, v160
	v_exp_f32_e32 v210, v161
	v_exp_f32_e32 v211, v162
	v_exp_f32_e32 v212, v163
	s_waitcnt lgkmcnt(4)
	v_mfma_f32_32x32x16_bf16 v[120:135], v[76:79], v[176:179], v[120:135]
	v_exp_f32_e32 v160, v164
	v_exp_f32_e32 v161, v165
	v_exp_f32_e32 v162, v166
	v_exp_f32_e32 v163, v167
	s_waitcnt lgkmcnt(3)
	v_mfma_f32_32x32x16_bf16 v[136:151], v[80:83], v[172:175], v[136:151]
	v_exp_f32_e32 v164, v96
	v_exp_f32_e32 v165, v97
	v_exp_f32_e32 v166, v98
	v_exp_f32_e32 v167, v99
	s_waitcnt lgkmcnt(2)
	v_mfma_f32_32x32x16_bf16 v[120:135], v[84:87], v[172:175], v[120:135]
	v_exp_f32_e32 v96, v100
	v_exp_f32_e32 v97, v101
	v_exp_f32_e32 v98, v102
	v_exp_f32_e32 v99, v103
	s_waitcnt lgkmcnt(1)
	v_mfma_f32_32x32x16_bf16 v[136:151], v[88:91], v[168:171], v[136:151]
	v_exp_f32_e32 v100, v104
	v_exp_f32_e32 v101, v105
	v_exp_f32_e32 v102, v106
	v_exp_f32_e32 v103, v107
	s_waitcnt lgkmcnt(0)
	v_mfma_f32_32x32x16_bf16 v[120:135], v[92:95], v[168:171], v[120:135]
	v_exp_f32_e32 v104, v108
	v_exp_f32_e32 v105, v109
	v_exp_f32_e32 v106, v110
	v_exp_f32_e32 v107, v111
	s_cmp_gt_i32 s27, 2
	s_cselect_b32 s34, -3, 2
	s_add_i32 s34, s34, s27
	s_mulk_i32 s34, 0x2400
	v_add_u32_e32 v88, s29, v195
	s_min_u32 s29, s13, s12
	s_waitcnt vmcnt(3)
	ds_write_b128 v208, v[10:13] offset:18432
	v_add_u32_e32 v10, s34, v208
	s_lshl_b32 s92, s29, 13
	s_waitcnt vmcnt(2)
	ds_write_b128 v10, v[112:115] offset:36864
	ds_read_b128 v[240:243], v195 offset:9216
	ds_read_b128 v[244:247], v195 offset:13824
	ds_read_b128 v[10:13], v88 offset:41472
	ds_read_b128 v[64:67], v88 offset:36864
	ds_read_b128 v[68:71], v88 offset:36896
	ds_read_b128 v[72:75], v88 offset:41504
	ds_read_b128 v[76:79], v88 offset:36928
	ds_read_b128 v[80:83], v88 offset:41536
	ds_read_b128 v[84:87], v88 offset:36960
	ds_read_b128 v[88:91], v88 offset:41568
	s_add_u32 vcc_lo, s100, s92
	s_addc_u32 vcc_hi, s101, 0
	global_load_dwordx4 v[152:155], v248, vcc
	s_lshl_b32 s92, s28, 7
	s_add_u32 vcc_lo, s98, s92
	s_addc_u32 vcc_hi, s99, 0
	global_load_dwordx4 v[156:159], v249, vcc
	v_add_f32_e32 v1, v1, v187
	s_setprio 1
	v_mov_b32_e32 v109, v136
	v_cvt_pk_bf16_f32 v92, v14, v15
	v_cvt_pk_bf16_f32 v93, v116, v117
	v_cvt_pk_bf16_f32 v94, v118, v119
	v_cvt_pk_bf16_f32 v95, v184, v185
	s_waitcnt lgkmcnt(6)
	s_nop 0
	v_mfma_f32_32x32x16_bf16 v[16:31], v[64:67], v[92:95], v[16:31]
	v_max3_f32 v109, v109, v137, v138
	v_max3_f32 v109, v109, v139, v140
	v_add_f32_e32 v108, v14, v15
	v_add_f32_e32 v108, v108, v116
	v_add_f32_e32 v108, v108, v117
	s_nop 0
	v_mfma_f32_32x32x16_bf16 v[32:47], v[10:13], v[92:95], v[32:47]
	v_cvt_pk_bf16_f32 v64, v186, v210
	v_cvt_pk_bf16_f32 v65, v211, v212
	v_cvt_pk_bf16_f32 v66, v160, v161
	v_cvt_pk_bf16_f32 v67, v162, v163
	v_max3_f32 v109, v109, v141, v142
	v_max3_f32 v109, v109, v143, v144
	v_add_f32_e32 v108, v108, v118
	v_add_f32_e32 v108, v108, v119
	v_add_f32_e32 v108, v108, v184
	v_add_f32_e32 v108, v108, v185
	s_waitcnt lgkmcnt(5)
	v_mfma_f32_32x32x16_bf16 v[16:31], v[68:71], v[64:67], v[16:31]
	v_max3_f32 v109, v109, v145, v146
	v_max3_f32 v109, v109, v147, v148
	v_add_f32_e32 v108, v108, v186
	v_add_f32_e32 v108, v108, v210
	v_add_f32_e32 v108, v108, v211
	v_add_f32_e32 v108, v108, v212
	s_waitcnt lgkmcnt(4)
	v_mfma_f32_32x32x16_bf16 v[32:47], v[72:75], v[64:67], v[32:47]
	v_cvt_pk_bf16_f32 v10, v164, v165
	v_cvt_pk_bf16_f32 v11, v166, v167
	v_cvt_pk_bf16_f32 v12, v96, v97
	v_cvt_pk_bf16_f32 v13, v98, v99
	v_max3_f32 v109, v109, v149, v150
	v_max3_f32 v109, v109, v151, v120
	v_add_f32_e32 v108, v108, v160
	v_add_f32_e32 v108, v108, v161
	v_add_f32_e32 v108, v108, v162
	v_add_f32_e32 v108, v108, v163
	s_waitcnt lgkmcnt(3)
	v_mfma_f32_32x32x16_bf16 v[16:31], v[76:79], v[10:13], v[16:31]
	v_max3_f32 v109, v109, v121, v122
	v_max3_f32 v109, v109, v123, v124
	v_add_f32_e32 v108, v108, v164
	v_add_f32_e32 v108, v108, v165
	v_add_f32_e32 v108, v108, v166
	v_add_f32_e32 v108, v108, v167
	s_waitcnt lgkmcnt(2)
	v_mfma_f32_32x32x16_bf16 v[32:47], v[80:83], v[10:13], v[32:47]
	v_cvt_pk_bf16_f32 v64, v100, v101
	v_cvt_pk_bf16_f32 v65, v102, v103
	v_cvt_pk_bf16_f32 v66, v104, v105
	v_cvt_pk_bf16_f32 v67, v106, v107
	v_max3_f32 v109, v109, v125, v126
	v_max3_f32 v109, v109, v127, v128
	v_add_f32_e32 v108, v108, v96
	v_add_f32_e32 v108, v108, v97
	v_add_f32_e32 v108, v108, v98
	v_add_f32_e32 v108, v108, v99
	s_waitcnt lgkmcnt(1)
	v_mfma_f32_32x32x16_bf16 v[16:31], v[84:87], v[64:67], v[16:31]
	v_max3_f32 v109, v109, v129, v130
	v_max3_f32 v109, v109, v131, v132
	v_add_f32_e32 v108, v108, v100
	v_add_f32_e32 v108, v108, v101
	v_add_f32_e32 v108, v108, v102
	v_add_f32_e32 v108, v108, v103
	s_waitcnt lgkmcnt(0)
	v_mfma_f32_32x32x16_bf16 v[32:47], v[88:91], v[64:67], v[32:47]
	v_max3_f32 v109, v109, v133, v134
	v_max3_f32 v109, v109, v135, v135
	v_add_f32_e32 v108, v108, v104
	v_add_f32_e32 v108, v108, v105
	v_add_f32_e32 v108, v108, v106
	v_add_f32_e32 v108, v108, v107
	s_setprio 0
	ds_read_b128 v[164:167], v195 offset:9248
	ds_read_b128 v[160:163], v195 offset:13856
	ds_read_b128 v[74:77], v195 offset:9280
	ds_read_b128 v[66:69], v195 offset:9312
	ds_read_b128 v[70:73], v195 offset:13888
	ds_read_b128 v[10:13], v195 offset:13920
	v_add_f32_e32 v64, v1, v108
	v_mov_b32_e32 v1, v109
	s_nop 1
	v_permlane32_swap_b32_e32 v109, v1
	v_max_f32_e32 v1, v1, v1
	v_max_f32_e32 v14, v109, v109
	v_max_f32_e32 v1, v14, v1
	v_cmp_lt_f32_e32 vcc, s52, v1
	s_cbranch_vccz .LBB0_663
	v_max_f32_e32 v1, v1, v1
	v_max_f32_e32 v14, 0, v1
	v_add_f32_e32 v209, v209, v14
	v_xor_b32_e32 v48, 0x80000000, v209
	v_pk_add_f32 v[136:137], v[136:137], v[14:15] op_sel_hi:[1,0] neg_lo:[0,1] neg_hi:[0,1]
	v_pk_add_f32 v[120:121], v[120:121], v[14:15] op_sel_hi:[1,0] neg_lo:[0,1] neg_hi:[0,1]
	v_pk_add_f32 v[138:139], v[138:139], v[14:15] op_sel_hi:[1,0] neg_lo:[0,1] neg_hi:[0,1]
	v_pk_add_f32 v[122:123], v[122:123], v[14:15] op_sel_hi:[1,0] neg_lo:[0,1] neg_hi:[0,1]
	v_pk_add_f32 v[140:141], v[140:141], v[14:15] op_sel_hi:[1,0] neg_lo:[0,1] neg_hi:[0,1]
	v_pk_add_f32 v[124:125], v[124:125], v[14:15] op_sel_hi:[1,0] neg_lo:[0,1] neg_hi:[0,1]
	v_pk_add_f32 v[142:143], v[142:143], v[14:15] op_sel_hi:[1,0] neg_lo:[0,1] neg_hi:[0,1]
	v_pk_add_f32 v[126:127], v[126:127], v[14:15] op_sel_hi:[1,0] neg_lo:[0,1] neg_hi:[0,1]
	v_pk_add_f32 v[144:145], v[144:145], v[14:15] op_sel_hi:[1,0] neg_lo:[0,1] neg_hi:[0,1]
	v_pk_add_f32 v[128:129], v[128:129], v[14:15] op_sel_hi:[1,0] neg_lo:[0,1] neg_hi:[0,1]
	v_pk_add_f32 v[146:147], v[146:147], v[14:15] op_sel_hi:[1,0] neg_lo:[0,1] neg_hi:[0,1]
	v_pk_add_f32 v[130:131], v[130:131], v[14:15] op_sel_hi:[1,0] neg_lo:[0,1] neg_hi:[0,1]
	v_pk_add_f32 v[148:149], v[148:149], v[14:15] op_sel_hi:[1,0] neg_lo:[0,1] neg_hi:[0,1]
	v_pk_add_f32 v[132:133], v[132:133], v[14:15] op_sel_hi:[1,0] neg_lo:[0,1] neg_hi:[0,1]
	v_pk_add_f32 v[150:151], v[150:151], v[14:15] op_sel_hi:[1,0] neg_lo:[0,1] neg_hi:[0,1]
	v_pk_add_f32 v[134:135], v[134:135], v[14:15] op_sel_hi:[1,0] neg_lo:[0,1] neg_hi:[0,1]
	v_exp_f32_e64 v14, -v14
	v_mov_b32_e32 v49, v48
	v_mov_b32_e32 v50, v48
	v_mov_b32_e32 v51, v48
	v_mov_b32_e32 v52, v48
	v_mov_b32_e32 v53, v48
	v_mov_b32_e32 v54, v48
	v_mov_b32_e32 v55, v48
	v_mov_b32_e32 v56, v48
	v_mov_b32_e32 v57, v48
	v_mov_b32_e32 v58, v48
	v_mov_b32_e32 v59, v48
	v_mov_b32_e32 v60, v48
	v_mov_b32_e32 v61, v48
	v_mov_b32_e32 v62, v48
	v_mov_b32_e32 v63, v48
	s_nop 11
	v_pk_mul_f32 v[30:31], v[30:31], v[14:15] op_sel_hi:[1,0]
	v_pk_mul_f32 v[28:29], v[28:29], v[14:15] op_sel_hi:[1,0]
	v_pk_mul_f32 v[26:27], v[26:27], v[14:15] op_sel_hi:[1,0]
	v_pk_mul_f32 v[24:25], v[24:25], v[14:15] op_sel_hi:[1,0]
	v_pk_mul_f32 v[22:23], v[22:23], v[14:15] op_sel_hi:[1,0]
	v_pk_mul_f32 v[20:21], v[20:21], v[14:15] op_sel_hi:[1,0]
	v_pk_mul_f32 v[18:19], v[18:19], v[14:15] op_sel_hi:[1,0]
	v_pk_mul_f32 v[16:17], v[16:17], v[14:15] op_sel_hi:[1,0]
	v_pk_mul_f32 v[46:47], v[46:47], v[14:15] op_sel_hi:[1,0]
	v_pk_mul_f32 v[44:45], v[44:45], v[14:15] op_sel_hi:[1,0]
	v_pk_mul_f32 v[42:43], v[42:43], v[14:15] op_sel_hi:[1,0]
	v_pk_mul_f32 v[40:41], v[40:41], v[14:15] op_sel_hi:[1,0]
	v_pk_mul_f32 v[38:39], v[38:39], v[14:15] op_sel_hi:[1,0]
	v_pk_mul_f32 v[36:37], v[36:37], v[14:15] op_sel_hi:[1,0]
	v_pk_mul_f32 v[34:35], v[34:35], v[14:15] op_sel_hi:[1,0]
	v_pk_mul_f32 v[32:33], v[32:33], v[14:15] op_sel_hi:[1,0]
	v_mul_f32_e32 v64, v64, v14
